# GEMM main loops: fragment LDS reads issued first in each load segment, loop pointer increments sunk into the last MFMA segment
# speedup vs baseline: 1.0073x; 1.0012x over previous
.LBB0_446:
	s_add_i32 s22, 0, 0x10000
	s_add_i32 s23, 0, 0x14000
	v_add_u32_e32 v134, s22, v191
	v_add_u32_e32 v162, s23, v191
	ds_read_b128 v[114:117], v134
	ds_read_b128 v[126:129], v134 offset:1024
	ds_read_b128 v[130:133], v134 offset:2048
	ds_read_b128 v[134:137], v134 offset:3072
	ds_read_b128 v[146:149], v162
	ds_read_b128 v[150:153], v162 offset:1024
	ds_read_b128 v[158:161], v162 offset:2048
	ds_read_b128 v[182:185], v162 offset:3072
	ds_read_b128 v[186:189], v193
	ds_read_b128 v[194:197], v193 offset:1024
	ds_read_b128 v[198:201], v193 offset:2048
	ds_read_b128 v[214:217], v193 offset:3072
	ds_read_b128 v[218:221], v193 offset:4096
	ds_read_b128 v[222:225], v193 offset:5120
	ds_read_b128 v[226:229], v193 offset:6144
	ds_read_b128 v[230:233], v193 offset:7168
	s_add_u32 s20, s56, 0xfff50080
	s_addc_u32 s21, s57, -1
	s_cmp_eq_u32 s84, 40
	s_cselect_b32 s61, s49, s21
	s_cselect_b32 s60, s48, s20
	s_cselect_b32 s21, s51, s63
	s_cselect_b32 s20, s50, s62
	v_lshl_add_u64 v[162:163], s[56:57], 0, v[156:157]
	s_add_i32 m0, s47, 0xc000
	s_nop 0
	global_load_lds_dwordx4 v[162:163], off
	v_lshl_add_u64 v[162:163], v[162:163], 0, s[2:3]
	s_add_i32 m0, s47, 0xe000
	s_nop 0
	global_load_lds_dwordx4 v[162:163], off
	s_waitcnt vmcnt(8)
	s_waitcnt lgkmcnt(0)
	s_barrier
	s_setprio 1
	s_waitcnt lgkmcnt(0)
	v_mfma_f32_16x16x32_bf16 v[142:145], v[114:117], v[186:189], v[142:145]
	v_mfma_f32_16x16x32_bf16 v[142:145], v[126:129], v[194:197], v[142:145]
	v_mfma_f32_16x16x32_bf16 v[138:141], v[130:133], v[186:189], v[138:141]
	v_mfma_f32_16x16x32_bf16 v[138:141], v[134:137], v[194:197], v[138:141]
	v_mfma_f32_16x16x32_bf16 v[110:113], v[114:117], v[198:201], v[110:113]
	v_mfma_f32_16x16x32_bf16 v[110:113], v[126:129], v[214:217], v[110:113]
	v_mfma_f32_16x16x32_bf16 v[106:109], v[130:133], v[198:201], v[106:109]
	v_mfma_f32_16x16x32_bf16 v[106:109], v[134:137], v[214:217], v[106:109]
	v_mfma_f32_16x16x32_bf16 v[94:97], v[114:117], v[218:221], v[94:97]
	v_mfma_f32_16x16x32_bf16 v[94:97], v[126:129], v[222:225], v[94:97]
	v_mfma_f32_16x16x32_bf16 v[90:93], v[130:133], v[218:221], v[90:93]
	v_mfma_f32_16x16x32_bf16 v[90:93], v[134:137], v[222:225], v[90:93]
	v_mfma_f32_16x16x32_bf16 v[78:81], v[114:117], v[226:229], v[78:81]
	v_mfma_f32_16x16x32_bf16 v[78:81], v[126:129], v[230:233], v[78:81]
	v_mfma_f32_16x16x32_bf16 v[74:77], v[130:133], v[226:229], v[74:77]
	v_mfma_f32_16x16x32_bf16 v[74:77], v[134:137], v[230:233], v[74:77]
	s_setprio 0
	s_setprio 1
	v_mfma_f32_16x16x32_bf16 v[122:125], v[146:149], v[186:189], v[122:125]
	v_mfma_f32_16x16x32_bf16 v[122:125], v[150:153], v[194:197], v[122:125]
	v_mfma_f32_16x16x32_bf16 v[118:121], v[158:161], v[186:189], v[118:121]
	v_mfma_f32_16x16x32_bf16 v[118:121], v[182:185], v[194:197], v[118:121]
	v_mfma_f32_16x16x32_bf16 v[102:105], v[146:149], v[198:201], v[102:105]
	v_mfma_f32_16x16x32_bf16 v[102:105], v[150:153], v[214:217], v[102:105]
	v_mfma_f32_16x16x32_bf16 v[98:101], v[158:161], v[198:201], v[98:101]
	v_mfma_f32_16x16x32_bf16 v[98:101], v[182:185], v[214:217], v[98:101]
	v_mfma_f32_16x16x32_bf16 v[86:89], v[146:149], v[218:221], v[86:89]
	v_mfma_f32_16x16x32_bf16 v[86:89], v[150:153], v[222:225], v[86:89]
	v_mfma_f32_16x16x32_bf16 v[82:85], v[158:161], v[218:221], v[82:85]
	v_mfma_f32_16x16x32_bf16 v[82:85], v[182:185], v[222:225], v[82:85]
	v_mfma_f32_16x16x32_bf16 v[70:73], v[146:149], v[226:229], v[70:73]
	v_mfma_f32_16x16x32_bf16 v[70:73], v[150:153], v[230:233], v[70:73]
	v_mfma_f32_16x16x32_bf16 v[66:69], v[158:161], v[226:229], v[66:69]
	v_mfma_f32_16x16x32_bf16 v[66:69], v[182:185], v[230:233], v[66:69]
	s_setprio 0
	s_barrier
	ds_read_b128 v[186:189], v193 offset:16384
	ds_read_b128 v[194:197], v193 offset:17408
	ds_read_b128 v[198:201], v193 offset:18432
	ds_read_b128 v[214:217], v193 offset:19456
	ds_read_b128 v[218:221], v193 offset:20480
	ds_read_b128 v[222:225], v193 offset:21504
	ds_read_b128 v[226:229], v193 offset:22528
	ds_read_b128 v[230:233], v193 offset:23552
	v_lshl_add_u64 v[162:163], s[20:21], 0, v[0:1]
	s_add_i32 s20, s22, s46
	s_mov_b32 m0, s20
	s_nop 0
	global_load_lds_dwordx4 v[162:163], off
	v_lshl_add_u64 v[202:203], v[162:163], 0, s[2:3]
	s_add_i32 m0, s20, 0x2000
	s_add_i32 s20, s23, s46
	global_load_lds_dwordx4 v[202:203], off
	v_lshl_add_u64 v[202:203], v[162:163], 0, s[12:13]
	s_mov_b32 m0, s20
	s_nop 0
	global_load_lds_dwordx4 v[202:203], off
	v_lshl_add_u64 v[202:203], v[162:163], 0, s[86:87]
	s_add_i32 m0, s20, 0x2000
	s_nop 0
	global_load_lds_dwordx4 v[202:203], off
	v_lshl_add_u64 v[202:203], s[60:61], 0, v[154:155]
	s_mov_b32 m0, s47
	v_lshl_add_u64 v[234:235], v[202:203], 0, s[2:3]
	global_load_lds_dwordx4 v[202:203], off
	s_mov_b32 m0, s68
	s_nop 0
	global_load_lds_dwordx4 v[234:235], off
	s_waitcnt vmcnt(8)
	s_waitcnt lgkmcnt(0)
	s_barrier
	s_setprio 1
	s_waitcnt lgkmcnt(0)
	v_mfma_f32_16x16x32_bf16 v[62:65], v[114:117], v[186:189], v[62:65]
	v_mfma_f32_16x16x32_bf16 v[62:65], v[126:129], v[194:197], v[62:65]
	v_mfma_f32_16x16x32_bf16 v[58:61], v[130:133], v[186:189], v[58:61]
	v_mfma_f32_16x16x32_bf16 v[58:61], v[134:137], v[194:197], v[58:61]
	v_mfma_f32_16x16x32_bf16 v[46:49], v[114:117], v[198:201], v[46:49]
	v_mfma_f32_16x16x32_bf16 v[46:49], v[126:129], v[214:217], v[46:49]
	v_mfma_f32_16x16x32_bf16 v[42:45], v[130:133], v[198:201], v[42:45]
	v_mfma_f32_16x16x32_bf16 v[42:45], v[134:137], v[214:217], v[42:45]
	v_mfma_f32_16x16x32_bf16 v[30:33], v[114:117], v[218:221], v[30:33]
	v_mfma_f32_16x16x32_bf16 v[30:33], v[126:129], v[222:225], v[30:33]
	v_mfma_f32_16x16x32_bf16 v[26:29], v[130:133], v[218:221], v[26:29]
	v_mfma_f32_16x16x32_bf16 v[26:29], v[134:137], v[222:225], v[26:29]
	v_mfma_f32_16x16x32_bf16 v[14:17], v[114:117], v[226:229], v[14:17]
	v_mfma_f32_16x16x32_bf16 v[14:17], v[126:129], v[230:233], v[14:17]
	v_mfma_f32_16x16x32_bf16 v[10:13], v[130:133], v[226:229], v[10:13]
	v_mfma_f32_16x16x32_bf16 v[10:13], v[134:137], v[230:233], v[10:13]
	s_setprio 0
	s_setprio 1
	v_mfma_f32_16x16x32_bf16 v[54:57], v[146:149], v[186:189], v[54:57]
	v_mfma_f32_16x16x32_bf16 v[54:57], v[150:153], v[194:197], v[54:57]
	v_mfma_f32_16x16x32_bf16 v[50:53], v[158:161], v[186:189], v[50:53]
	v_mfma_f32_16x16x32_bf16 v[50:53], v[182:185], v[194:197], v[50:53]
	v_mfma_f32_16x16x32_bf16 v[38:41], v[146:149], v[198:201], v[38:41]
	v_mfma_f32_16x16x32_bf16 v[38:41], v[150:153], v[214:217], v[38:41]
	v_mfma_f32_16x16x32_bf16 v[34:37], v[158:161], v[198:201], v[34:37]
	v_mfma_f32_16x16x32_bf16 v[34:37], v[182:185], v[214:217], v[34:37]
	v_mfma_f32_16x16x32_bf16 v[22:25], v[146:149], v[218:221], v[22:25]
	v_mfma_f32_16x16x32_bf16 v[22:25], v[150:153], v[222:225], v[22:25]
	v_mfma_f32_16x16x32_bf16 v[18:21], v[158:161], v[218:221], v[18:21]
	v_mfma_f32_16x16x32_bf16 v[18:21], v[182:185], v[222:225], v[18:21]
	v_mfma_f32_16x16x32_bf16 v[6:9], v[146:149], v[226:229], v[6:9]
	v_mfma_f32_16x16x32_bf16 v[6:9], v[150:153], v[230:233], v[6:9]
	v_mfma_f32_16x16x32_bf16 v[2:5], v[158:161], v[226:229], v[2:5]
	v_mfma_f32_16x16x32_bf16 v[2:5], v[182:185], v[230:233], v[2:5]
	s_setprio 0
	s_barrier
	s_add_i32 s20, 0, 0x18000
	s_add_i32 s21, 0, 0x1c000
	v_add_u32_e32 v134, s20, v191
	v_add_u32_e32 v182, s21, v191
	ds_read_b128 v[114:117], v134
	ds_read_b128 v[126:129], v134 offset:1024
	ds_read_b128 v[130:133], v134 offset:2048
	ds_read_b128 v[134:137], v134 offset:3072
	ds_read_b128 v[146:149], v182
	ds_read_b128 v[150:153], v182 offset:1024
	ds_read_b128 v[158:161], v182 offset:2048
	ds_read_b128 v[182:185], v182 offset:3072
	ds_read_b128 v[186:189], v193 offset:32768
	ds_read_b128 v[194:197], v193 offset:33792
	ds_read_b128 v[198:201], v193 offset:34816
	ds_read_b128 v[214:217], v193 offset:35840
	ds_read_b128 v[218:221], v193 offset:36864
	ds_read_b128 v[222:225], v193 offset:37888
	ds_read_b128 v[226:229], v193 offset:38912
	ds_read_b128 v[230:233], v193 offset:39936
	s_mov_b32 m0, s69
	v_lshl_add_u64 v[234:235], v[202:203], 0, s[12:13]
	global_load_lds_dwordx4 v[234:235], off
	v_lshl_add_u64 v[234:235], v[202:203], 0, s[86:87]
	s_mov_b32 m0, s76
	s_nop 0
	global_load_lds_dwordx4 v[234:235], off
	s_waitcnt vmcnt(8)
	s_waitcnt lgkmcnt(0)
	s_barrier
	s_setprio 1
	s_waitcnt lgkmcnt(0)
	v_mfma_f32_16x16x32_bf16 v[142:145], v[114:117], v[186:189], v[142:145]
	v_mfma_f32_16x16x32_bf16 v[142:145], v[126:129], v[194:197], v[142:145]
	v_mfma_f32_16x16x32_bf16 v[138:141], v[130:133], v[186:189], v[138:141]
	v_mfma_f32_16x16x32_bf16 v[138:141], v[134:137], v[194:197], v[138:141]
	v_mfma_f32_16x16x32_bf16 v[110:113], v[114:117], v[198:201], v[110:113]
	v_mfma_f32_16x16x32_bf16 v[110:113], v[126:129], v[214:217], v[110:113]
	v_mfma_f32_16x16x32_bf16 v[106:109], v[130:133], v[198:201], v[106:109]
	v_mfma_f32_16x16x32_bf16 v[106:109], v[134:137], v[214:217], v[106:109]
	v_mfma_f32_16x16x32_bf16 v[94:97], v[114:117], v[218:221], v[94:97]
	v_mfma_f32_16x16x32_bf16 v[94:97], v[126:129], v[222:225], v[94:97]
	v_mfma_f32_16x16x32_bf16 v[90:93], v[130:133], v[218:221], v[90:93]
	v_mfma_f32_16x16x32_bf16 v[90:93], v[134:137], v[222:225], v[90:93]
	v_mfma_f32_16x16x32_bf16 v[78:81], v[114:117], v[226:229], v[78:81]
	v_mfma_f32_16x16x32_bf16 v[78:81], v[126:129], v[230:233], v[78:81]
	v_mfma_f32_16x16x32_bf16 v[74:77], v[130:133], v[226:229], v[74:77]
	v_mfma_f32_16x16x32_bf16 v[74:77], v[134:137], v[230:233], v[74:77]
	s_setprio 0
	s_setprio 1
	v_mfma_f32_16x16x32_bf16 v[122:125], v[146:149], v[186:189], v[122:125]
	v_mfma_f32_16x16x32_bf16 v[122:125], v[150:153], v[194:197], v[122:125]
	v_mfma_f32_16x16x32_bf16 v[118:121], v[158:161], v[186:189], v[118:121]
	v_mfma_f32_16x16x32_bf16 v[118:121], v[182:185], v[194:197], v[118:121]
	v_mfma_f32_16x16x32_bf16 v[102:105], v[146:149], v[198:201], v[102:105]
	v_mfma_f32_16x16x32_bf16 v[102:105], v[150:153], v[214:217], v[102:105]
	v_mfma_f32_16x16x32_bf16 v[98:101], v[158:161], v[198:201], v[98:101]
	v_mfma_f32_16x16x32_bf16 v[98:101], v[182:185], v[214:217], v[98:101]
	v_mfma_f32_16x16x32_bf16 v[86:89], v[146:149], v[218:221], v[86:89]
	v_mfma_f32_16x16x32_bf16 v[86:89], v[150:153], v[222:225], v[86:89]
	v_mfma_f32_16x16x32_bf16 v[82:85], v[158:161], v[218:221], v[82:85]
	v_mfma_f32_16x16x32_bf16 v[82:85], v[182:185], v[222:225], v[82:85]
	v_mfma_f32_16x16x32_bf16 v[70:73], v[146:149], v[226:229], v[70:73]
	v_mfma_f32_16x16x32_bf16 v[70:73], v[150:153], v[230:233], v[70:73]
	v_mfma_f32_16x16x32_bf16 v[66:69], v[158:161], v[226:229], v[66:69]
	v_mfma_f32_16x16x32_bf16 v[66:69], v[182:185], v[230:233], v[66:69]
	s_setprio 0
	s_barrier
	ds_read_b128 v[186:189], v193 offset:49152
	ds_read_b128 v[194:197], v193 offset:50176
	ds_read_b128 v[198:201], v193 offset:51200
	ds_read_b128 v[214:217], v193 offset:52224
	ds_read_b128 v[218:221], v193 offset:53248
	ds_read_b128 v[222:225], v193 offset:54272
	ds_read_b128 v[226:229], v193 offset:55296
	ds_read_b128 v[230:233], v193 offset:56320
	s_add_i32 s20, s20, s46
	v_lshl_add_u64 v[234:235], v[162:163], 0, s[34:35]
	s_mov_b32 m0, s20
	s_nop 0
	global_load_lds_dwordx4 v[234:235], off
	v_lshl_add_u64 v[234:235], v[162:163], 0, s[96:97]
	s_add_i32 m0, s20, 0x2000
	s_add_i32 s20, s21, s46
	global_load_lds_dwordx4 v[234:235], off
	v_lshl_add_u64 v[234:235], v[162:163], 0, vcc
	s_mov_b32 m0, s20
	v_lshl_add_u64 v[162:163], v[162:163], 0, s[0:1]
	global_load_lds_dwordx4 v[234:235], off
	s_add_i32 m0, s20, 0x2000
	s_nop 0
	global_load_lds_dwordx4 v[162:163], off
	v_lshl_add_u64 v[162:163], v[202:203], 0, s[34:35]
	s_mov_b32 m0, s77
	s_nop 0
	global_load_lds_dwordx4 v[162:163], off
	v_lshl_add_u64 v[162:163], v[202:203], 0, s[96:97]
	s_mov_b32 m0, s78
	s_nop 0
	global_load_lds_dwordx4 v[162:163], off
	s_waitcnt vmcnt(8)
	s_waitcnt lgkmcnt(0)
	s_barrier
	s_setprio 1
	s_waitcnt lgkmcnt(0)
	v_mfma_f32_16x16x32_bf16 v[62:65], v[114:117], v[186:189], v[62:65]
	v_mfma_f32_16x16x32_bf16 v[62:65], v[126:129], v[194:197], v[62:65]
	v_mfma_f32_16x16x32_bf16 v[58:61], v[130:133], v[186:189], v[58:61]
	v_mfma_f32_16x16x32_bf16 v[58:61], v[134:137], v[194:197], v[58:61]
	v_mfma_f32_16x16x32_bf16 v[46:49], v[114:117], v[198:201], v[46:49]
	v_mfma_f32_16x16x32_bf16 v[46:49], v[126:129], v[214:217], v[46:49]
	v_mfma_f32_16x16x32_bf16 v[42:45], v[130:133], v[198:201], v[42:45]
	v_mfma_f32_16x16x32_bf16 v[42:45], v[134:137], v[214:217], v[42:45]
	v_mfma_f32_16x16x32_bf16 v[30:33], v[114:117], v[218:221], v[30:33]
	v_mfma_f32_16x16x32_bf16 v[30:33], v[126:129], v[222:225], v[30:33]
	v_mfma_f32_16x16x32_bf16 v[26:29], v[130:133], v[218:221], v[26:29]
	v_mfma_f32_16x16x32_bf16 v[26:29], v[134:137], v[222:225], v[26:29]
	v_mfma_f32_16x16x32_bf16 v[14:17], v[114:117], v[226:229], v[14:17]
	v_mfma_f32_16x16x32_bf16 v[14:17], v[126:129], v[230:233], v[14:17]
	v_mfma_f32_16x16x32_bf16 v[10:13], v[130:133], v[226:229], v[10:13]
	v_mfma_f32_16x16x32_bf16 v[10:13], v[134:137], v[230:233], v[10:13]
	s_add_i32 s84, s84, 2
	s_add_u32 s56, s56, 0x100
	s_addc_u32 s57, s57, 0
	s_add_u32 s62, s62, 0x100
	s_addc_u32 s63, s63, 0
	s_setprio 0
	s_setprio 1
	v_mfma_f32_16x16x32_bf16 v[54:57], v[146:149], v[186:189], v[54:57]
	v_mfma_f32_16x16x32_bf16 v[54:57], v[150:153], v[194:197], v[54:57]
	v_mfma_f32_16x16x32_bf16 v[50:53], v[158:161], v[186:189], v[50:53]
	v_mfma_f32_16x16x32_bf16 v[50:53], v[182:185], v[194:197], v[50:53]
	v_mfma_f32_16x16x32_bf16 v[38:41], v[146:149], v[198:201], v[38:41]
	v_mfma_f32_16x16x32_bf16 v[38:41], v[150:153], v[214:217], v[38:41]
	v_mfma_f32_16x16x32_bf16 v[34:37], v[158:161], v[198:201], v[34:37]
	v_mfma_f32_16x16x32_bf16 v[34:37], v[182:185], v[214:217], v[34:37]
	v_mfma_f32_16x16x32_bf16 v[22:25], v[146:149], v[218:221], v[22:25]
	v_mfma_f32_16x16x32_bf16 v[22:25], v[150:153], v[222:225], v[22:25]
	v_mfma_f32_16x16x32_bf16 v[18:21], v[158:161], v[218:221], v[18:21]
	v_mfma_f32_16x16x32_bf16 v[18:21], v[182:185], v[222:225], v[18:21]
	v_mfma_f32_16x16x32_bf16 v[6:9], v[146:149], v[226:229], v[6:9]
	v_mfma_f32_16x16x32_bf16 v[6:9], v[150:153], v[230:233], v[6:9]
	v_mfma_f32_16x16x32_bf16 v[2:5], v[158:161], v[226:229], v[2:5]
	v_mfma_f32_16x16x32_bf16 v[2:5], v[182:185], v[230:233], v[2:5]
	s_setprio 0
	s_barrier
	s_cmp_gt_u32 s84, 41
	s_cbranch_scc0 .LBB0_446
	s_and_b64 vcc, exec, s[40:41]
	s_cbranch_vccz .LBB0_449
	s_barrier

.LBB0_488:
	s_add_i32 s22, 0, 0x10000
	v_add_u32_e32 v143, s22, v139
	s_add_i32 s23, 0, 0x14000
	ds_read_b128 v[134:137], v143
	ds_read_b128 v[144:147], v143 offset:1024
	ds_read_b128 v[148:151], v143 offset:2048
	ds_read_b128 v[152:155], v143 offset:3072
	v_add_u32_e32 v143, s23, v139
	ds_read_b128 v[156:159], v143
	ds_read_b128 v[160:163], v143 offset:1024
	ds_read_b128 v[182:185], v143 offset:2048
	ds_read_b128 v[186:189], v143 offset:3072
	ds_read_b128 v[190:193], v142
	ds_read_b128 v[194:197], v142 offset:1024
	ds_read_b128 v[198:201], v142 offset:2048
	ds_read_b128 v[214:217], v142 offset:3072
	ds_read_b128 v[218:221], v142 offset:4096
	ds_read_b128 v[222:225], v142 offset:5120
	ds_read_b128 v[226:229], v142 offset:6144
	ds_read_b128 v[230:233], v142 offset:7168
	s_add_u32 s20, s68, 0xfffc0080
	s_addc_u32 s21, s69, -1
	s_cmp_eq_u32 s97, 12
	s_cselect_b32 s77, s57, s21
	s_cselect_b32 s76, s86, s20
	s_cselect_b32 s21, s51, s96
	s_cselect_b32 s20, s87, s91
	v_lshl_add_u64 v[202:203], s[68:69], 0, v[132:133]
	s_add_i32 m0, s43, 0xc000
	s_nop 0
	global_load_lds_dwordx4 v[202:203], off
	v_lshl_add_u64 v[202:203], v[202:203], 0, s[72:73]
	s_add_i32 m0, s43, 0xe000
	s_nop 0
	global_load_lds_dwordx4 v[202:203], off
	s_waitcnt vmcnt(8)
	s_waitcnt lgkmcnt(0)
	s_barrier
	s_setprio 1
	s_waitcnt lgkmcnt(0)
	v_mfma_f32_16x16x32_bf16 v[126:129], v[134:137], v[190:193], v[126:129]
	v_mfma_f32_16x16x32_bf16 v[126:129], v[144:147], v[194:197], v[126:129]
	v_mfma_f32_16x16x32_bf16 v[114:117], v[148:151], v[190:193], v[114:117]
	v_mfma_f32_16x16x32_bf16 v[114:117], v[152:155], v[194:197], v[114:117]
	v_mfma_f32_16x16x32_bf16 v[110:113], v[134:137], v[198:201], v[110:113]
	v_mfma_f32_16x16x32_bf16 v[110:113], v[144:147], v[214:217], v[110:113]
	v_mfma_f32_16x16x32_bf16 v[98:101], v[148:151], v[198:201], v[98:101]
	v_mfma_f32_16x16x32_bf16 v[98:101], v[152:155], v[214:217], v[98:101]
	v_mfma_f32_16x16x32_bf16 v[94:97], v[134:137], v[218:221], v[94:97]
	v_mfma_f32_16x16x32_bf16 v[94:97], v[144:147], v[222:225], v[94:97]
	v_mfma_f32_16x16x32_bf16 v[82:85], v[148:151], v[218:221], v[82:85]
	v_mfma_f32_16x16x32_bf16 v[82:85], v[152:155], v[222:225], v[82:85]
	v_mfma_f32_16x16x32_bf16 v[78:81], v[134:137], v[226:229], v[78:81]
	v_mfma_f32_16x16x32_bf16 v[78:81], v[144:147], v[230:233], v[78:81]
	v_mfma_f32_16x16x32_bf16 v[66:69], v[148:151], v[226:229], v[66:69]
	v_mfma_f32_16x16x32_bf16 v[66:69], v[152:155], v[230:233], v[66:69]
	s_setprio 0
	s_setprio 1
	v_mfma_f32_16x16x32_bf16 v[122:125], v[156:159], v[190:193], v[122:125]
	v_mfma_f32_16x16x32_bf16 v[122:125], v[160:163], v[194:197], v[122:125]
	v_mfma_f32_16x16x32_bf16 v[118:121], v[182:185], v[190:193], v[118:121]
	v_mfma_f32_16x16x32_bf16 v[118:121], v[186:189], v[194:197], v[118:121]
	v_mfma_f32_16x16x32_bf16 v[106:109], v[156:159], v[198:201], v[106:109]
	v_mfma_f32_16x16x32_bf16 v[106:109], v[160:163], v[214:217], v[106:109]
	v_mfma_f32_16x16x32_bf16 v[102:105], v[182:185], v[198:201], v[102:105]
	v_mfma_f32_16x16x32_bf16 v[102:105], v[186:189], v[214:217], v[102:105]
	v_mfma_f32_16x16x32_bf16 v[90:93], v[156:159], v[218:221], v[90:93]
	v_mfma_f32_16x16x32_bf16 v[90:93], v[160:163], v[222:225], v[90:93]
	v_mfma_f32_16x16x32_bf16 v[86:89], v[182:185], v[218:221], v[86:89]
	v_mfma_f32_16x16x32_bf16 v[86:89], v[186:189], v[222:225], v[86:89]
	v_mfma_f32_16x16x32_bf16 v[74:77], v[156:159], v[226:229], v[74:77]
	v_mfma_f32_16x16x32_bf16 v[74:77], v[160:163], v[230:233], v[74:77]
	v_mfma_f32_16x16x32_bf16 v[70:73], v[182:185], v[226:229], v[70:73]
	v_mfma_f32_16x16x32_bf16 v[70:73], v[186:189], v[230:233], v[70:73]
	s_setprio 0
	s_barrier
	ds_read_b128 v[190:193], v142 offset:16384
	ds_read_b128 v[194:197], v142 offset:17408
	ds_read_b128 v[198:201], v142 offset:18432
	ds_read_b128 v[214:217], v142 offset:19456
	ds_read_b128 v[218:221], v142 offset:20480
	ds_read_b128 v[222:225], v142 offset:21504
	ds_read_b128 v[226:229], v142 offset:22528
	ds_read_b128 v[230:233], v142 offset:23552
	v_lshl_add_u64 v[202:203], s[20:21], 0, v[0:1]
	s_add_i32 s20, s22, s14
	s_mov_b32 m0, s20
	s_nop 0
	global_load_lds_dwordx4 v[202:203], off
	v_lshl_add_u64 v[234:235], v[202:203], 0, s[72:73]
	s_add_i32 m0, s20, 0x2000
	s_add_i32 s20, s23, s14
	global_load_lds_dwordx4 v[234:235], off
	v_lshl_add_u64 v[234:235], v[202:203], 0, s[28:29]
	s_mov_b32 m0, s20
	s_nop 0
	global_load_lds_dwordx4 v[234:235], off
	v_lshl_add_u64 v[234:235], v[202:203], 0, s[82:83]
	s_add_i32 m0, s20, 0x2000
	s_nop 0
	global_load_lds_dwordx4 v[234:235], off
	v_lshl_add_u64 v[234:235], s[76:77], 0, v[130:131]
	s_mov_b32 m0, s43
	v_lshl_add_u64 v[236:237], v[234:235], 0, s[72:73]
	global_load_lds_dwordx4 v[234:235], off
	s_mov_b32 m0, s46
	s_nop 0
	global_load_lds_dwordx4 v[236:237], off
	s_waitcnt vmcnt(8)
	s_waitcnt lgkmcnt(0)
	s_barrier
	s_setprio 1
	s_waitcnt lgkmcnt(0)
	v_mfma_f32_16x16x32_bf16 v[62:65], v[134:137], v[190:193], v[62:65]
	v_mfma_f32_16x16x32_bf16 v[62:65], v[144:147], v[194:197], v[62:65]
	v_mfma_f32_16x16x32_bf16 v[50:53], v[148:151], v[190:193], v[50:53]
	v_mfma_f32_16x16x32_bf16 v[50:53], v[152:155], v[194:197], v[50:53]
	v_mfma_f32_16x16x32_bf16 v[46:49], v[134:137], v[198:201], v[46:49]
	v_mfma_f32_16x16x32_bf16 v[46:49], v[144:147], v[214:217], v[46:49]
	v_mfma_f32_16x16x32_bf16 v[34:37], v[148:151], v[198:201], v[34:37]
	v_mfma_f32_16x16x32_bf16 v[34:37], v[152:155], v[214:217], v[34:37]
	v_mfma_f32_16x16x32_bf16 v[30:33], v[134:137], v[218:221], v[30:33]
	v_mfma_f32_16x16x32_bf16 v[30:33], v[144:147], v[222:225], v[30:33]
	v_mfma_f32_16x16x32_bf16 v[18:21], v[148:151], v[218:221], v[18:21]
	v_mfma_f32_16x16x32_bf16 v[18:21], v[152:155], v[222:225], v[18:21]
	v_mfma_f32_16x16x32_bf16 v[14:17], v[134:137], v[226:229], v[14:17]
	v_mfma_f32_16x16x32_bf16 v[14:17], v[144:147], v[230:233], v[14:17]
	v_mfma_f32_16x16x32_bf16 v[6:9], v[148:151], v[226:229], v[6:9]
	v_mfma_f32_16x16x32_bf16 v[6:9], v[152:155], v[230:233], v[6:9]
	s_setprio 0
	s_setprio 1
	v_mfma_f32_16x16x32_bf16 v[58:61], v[156:159], v[190:193], v[58:61]
	v_mfma_f32_16x16x32_bf16 v[58:61], v[160:163], v[194:197], v[58:61]
	v_mfma_f32_16x16x32_bf16 v[54:57], v[182:185], v[190:193], v[54:57]
	v_mfma_f32_16x16x32_bf16 v[54:57], v[186:189], v[194:197], v[54:57]
	v_mfma_f32_16x16x32_bf16 v[42:45], v[156:159], v[198:201], v[42:45]
	v_mfma_f32_16x16x32_bf16 v[42:45], v[160:163], v[214:217], v[42:45]
	v_mfma_f32_16x16x32_bf16 v[38:41], v[182:185], v[198:201], v[38:41]
	v_mfma_f32_16x16x32_bf16 v[38:41], v[186:189], v[214:217], v[38:41]
	v_mfma_f32_16x16x32_bf16 v[26:29], v[156:159], v[218:221], v[26:29]
	v_mfma_f32_16x16x32_bf16 v[26:29], v[160:163], v[222:225], v[26:29]
	v_mfma_f32_16x16x32_bf16 v[22:25], v[182:185], v[218:221], v[22:25]
	v_mfma_f32_16x16x32_bf16 v[22:25], v[186:189], v[222:225], v[22:25]
	v_mfma_f32_16x16x32_bf16 v[10:13], v[156:159], v[226:229], v[10:13]
	v_mfma_f32_16x16x32_bf16 v[10:13], v[160:163], v[230:233], v[10:13]
	v_mfma_f32_16x16x32_bf16 v[2:5], v[182:185], v[226:229], v[2:5]
	v_mfma_f32_16x16x32_bf16 v[2:5], v[186:189], v[230:233], v[2:5]
	s_setprio 0
	s_barrier
	s_add_i32 s20, 0, 0x18000
	v_add_u32_e32 v143, s20, v139
	s_add_i32 s21, 0, 0x1c000
	ds_read_b128 v[134:137], v143
	ds_read_b128 v[144:147], v143 offset:1024
	ds_read_b128 v[148:151], v143 offset:2048
	ds_read_b128 v[152:155], v143 offset:3072
	v_add_u32_e32 v143, s21, v139
	ds_read_b128 v[156:159], v143
	ds_read_b128 v[160:163], v143 offset:1024
	ds_read_b128 v[182:185], v143 offset:2048
	ds_read_b128 v[186:189], v143 offset:3072
	ds_read_b128 v[190:193], v142 offset:32768
	ds_read_b128 v[194:197], v142 offset:33792
	ds_read_b128 v[198:201], v142 offset:34816
	ds_read_b128 v[214:217], v142 offset:35840
	ds_read_b128 v[218:221], v142 offset:36864
	ds_read_b128 v[222:225], v142 offset:37888
	ds_read_b128 v[226:229], v142 offset:38912
	ds_read_b128 v[230:233], v142 offset:39936
	s_mov_b32 m0, s47
	v_lshl_add_u64 v[236:237], v[234:235], 0, s[28:29]
	global_load_lds_dwordx4 v[236:237], off
	v_lshl_add_u64 v[236:237], v[234:235], 0, s[82:83]
	s_mov_b32 m0, s78
	s_nop 0
	global_load_lds_dwordx4 v[236:237], off
	s_waitcnt vmcnt(8)
	s_waitcnt lgkmcnt(0)
	s_barrier
	s_setprio 1
	s_waitcnt lgkmcnt(0)
	v_mfma_f32_16x16x32_bf16 v[126:129], v[134:137], v[190:193], v[126:129]
	v_mfma_f32_16x16x32_bf16 v[126:129], v[144:147], v[194:197], v[126:129]
	v_mfma_f32_16x16x32_bf16 v[114:117], v[148:151], v[190:193], v[114:117]
	v_mfma_f32_16x16x32_bf16 v[114:117], v[152:155], v[194:197], v[114:117]
	v_mfma_f32_16x16x32_bf16 v[110:113], v[134:137], v[198:201], v[110:113]
	v_mfma_f32_16x16x32_bf16 v[110:113], v[144:147], v[214:217], v[110:113]
	v_mfma_f32_16x16x32_bf16 v[98:101], v[148:151], v[198:201], v[98:101]
	v_mfma_f32_16x16x32_bf16 v[98:101], v[152:155], v[214:217], v[98:101]
	v_mfma_f32_16x16x32_bf16 v[94:97], v[134:137], v[218:221], v[94:97]
	v_mfma_f32_16x16x32_bf16 v[94:97], v[144:147], v[222:225], v[94:97]
	v_mfma_f32_16x16x32_bf16 v[82:85], v[148:151], v[218:221], v[82:85]
	v_mfma_f32_16x16x32_bf16 v[82:85], v[152:155], v[222:225], v[82:85]
	v_mfma_f32_16x16x32_bf16 v[78:81], v[134:137], v[226:229], v[78:81]
	v_mfma_f32_16x16x32_bf16 v[78:81], v[144:147], v[230:233], v[78:81]
	v_mfma_f32_16x16x32_bf16 v[66:69], v[148:151], v[226:229], v[66:69]
	v_mfma_f32_16x16x32_bf16 v[66:69], v[152:155], v[230:233], v[66:69]
	s_setprio 0
	s_setprio 1
	v_mfma_f32_16x16x32_bf16 v[122:125], v[156:159], v[190:193], v[122:125]
	v_mfma_f32_16x16x32_bf16 v[122:125], v[160:163], v[194:197], v[122:125]
	v_mfma_f32_16x16x32_bf16 v[118:121], v[182:185], v[190:193], v[118:121]
	v_mfma_f32_16x16x32_bf16 v[118:121], v[186:189], v[194:197], v[118:121]
	v_mfma_f32_16x16x32_bf16 v[106:109], v[156:159], v[198:201], v[106:109]
	v_mfma_f32_16x16x32_bf16 v[106:109], v[160:163], v[214:217], v[106:109]
	v_mfma_f32_16x16x32_bf16 v[102:105], v[182:185], v[198:201], v[102:105]
	v_mfma_f32_16x16x32_bf16 v[102:105], v[186:189], v[214:217], v[102:105]
	v_mfma_f32_16x16x32_bf16 v[90:93], v[156:159], v[218:221], v[90:93]
	v_mfma_f32_16x16x32_bf16 v[90:93], v[160:163], v[222:225], v[90:93]
	v_mfma_f32_16x16x32_bf16 v[86:89], v[182:185], v[218:221], v[86:89]
	v_mfma_f32_16x16x32_bf16 v[86:89], v[186:189], v[222:225], v[86:89]
	v_mfma_f32_16x16x32_bf16 v[74:77], v[156:159], v[226:229], v[74:77]
	v_mfma_f32_16x16x32_bf16 v[74:77], v[160:163], v[230:233], v[74:77]
	v_mfma_f32_16x16x32_bf16 v[70:73], v[182:185], v[226:229], v[70:73]
	v_mfma_f32_16x16x32_bf16 v[70:73], v[186:189], v[230:233], v[70:73]
	s_setprio 0
	s_barrier
	ds_read_b128 v[190:193], v142 offset:49152
	ds_read_b128 v[194:197], v142 offset:50176
	ds_read_b128 v[198:201], v142 offset:51200
	ds_read_b128 v[214:217], v142 offset:52224
	ds_read_b128 v[218:221], v142 offset:53248
	ds_read_b128 v[222:225], v142 offset:54272
	ds_read_b128 v[226:229], v142 offset:55296
	ds_read_b128 v[230:233], v142 offset:56320
	s_add_i32 s20, s20, s14
	v_lshl_add_u64 v[236:237], v[202:203], 0, s[34:35]
	s_mov_b32 m0, s20
	s_nop 0
	global_load_lds_dwordx4 v[236:237], off
	v_lshl_add_u64 v[236:237], v[202:203], 0, s[38:39]
	s_add_i32 m0, s20, 0x2000
	s_add_i32 s20, s21, s14
	global_load_lds_dwordx4 v[236:237], off
	v_lshl_add_u64 v[236:237], v[202:203], 0, s[44:45]
	s_mov_b32 m0, s20
	v_lshl_add_u64 v[202:203], v[202:203], 0, s[10:11]
	global_load_lds_dwordx4 v[236:237], off
	s_add_i32 m0, s20, 0x2000
	s_nop 0
	global_load_lds_dwordx4 v[202:203], off
	v_lshl_add_u64 v[202:203], v[234:235], 0, s[34:35]
	s_mov_b32 m0, s79
	s_nop 0
	global_load_lds_dwordx4 v[202:203], off
	v_lshl_add_u64 v[202:203], v[234:235], 0, s[38:39]
	s_mov_b32 m0, s88
	s_nop 0
	global_load_lds_dwordx4 v[202:203], off
	s_waitcnt vmcnt(8)
	s_waitcnt lgkmcnt(0)
	s_barrier
	s_setprio 1
	s_waitcnt lgkmcnt(0)
	v_mfma_f32_16x16x32_bf16 v[62:65], v[134:137], v[190:193], v[62:65]
	v_mfma_f32_16x16x32_bf16 v[62:65], v[144:147], v[194:197], v[62:65]
	v_mfma_f32_16x16x32_bf16 v[50:53], v[148:151], v[190:193], v[50:53]
	v_mfma_f32_16x16x32_bf16 v[50:53], v[152:155], v[194:197], v[50:53]
	v_mfma_f32_16x16x32_bf16 v[46:49], v[134:137], v[198:201], v[46:49]
	v_mfma_f32_16x16x32_bf16 v[46:49], v[144:147], v[214:217], v[46:49]
	v_mfma_f32_16x16x32_bf16 v[34:37], v[148:151], v[198:201], v[34:37]
	v_mfma_f32_16x16x32_bf16 v[34:37], v[152:155], v[214:217], v[34:37]
	v_mfma_f32_16x16x32_bf16 v[30:33], v[134:137], v[218:221], v[30:33]
	v_mfma_f32_16x16x32_bf16 v[30:33], v[144:147], v[222:225], v[30:33]
	v_mfma_f32_16x16x32_bf16 v[18:21], v[148:151], v[218:221], v[18:21]
	v_mfma_f32_16x16x32_bf16 v[18:21], v[152:155], v[222:225], v[18:21]
	v_mfma_f32_16x16x32_bf16 v[14:17], v[134:137], v[226:229], v[14:17]
	v_mfma_f32_16x16x32_bf16 v[14:17], v[144:147], v[230:233], v[14:17]
	v_mfma_f32_16x16x32_bf16 v[6:9], v[148:151], v[226:229], v[6:9]
	v_mfma_f32_16x16x32_bf16 v[6:9], v[152:155], v[230:233], v[6:9]
	s_add_i32 s97, s97, 2
	s_add_u32 s68, s68, 0x100
	s_addc_u32 s69, s69, 0
	s_add_u32 s91, s91, 0x100
	s_addc_u32 s96, s96, 0
	s_setprio 0
	s_setprio 1
	v_mfma_f32_16x16x32_bf16 v[58:61], v[156:159], v[190:193], v[58:61]
	v_mfma_f32_16x16x32_bf16 v[58:61], v[160:163], v[194:197], v[58:61]
	v_mfma_f32_16x16x32_bf16 v[54:57], v[182:185], v[190:193], v[54:57]
	v_mfma_f32_16x16x32_bf16 v[54:57], v[186:189], v[194:197], v[54:57]
	v_mfma_f32_16x16x32_bf16 v[42:45], v[156:159], v[198:201], v[42:45]
	v_mfma_f32_16x16x32_bf16 v[42:45], v[160:163], v[214:217], v[42:45]
	v_mfma_f32_16x16x32_bf16 v[38:41], v[182:185], v[198:201], v[38:41]
	v_mfma_f32_16x16x32_bf16 v[38:41], v[186:189], v[214:217], v[38:41]
	v_mfma_f32_16x16x32_bf16 v[26:29], v[156:159], v[218:221], v[26:29]
	v_mfma_f32_16x16x32_bf16 v[26:29], v[160:163], v[222:225], v[26:29]
	v_mfma_f32_16x16x32_bf16 v[22:25], v[182:185], v[218:221], v[22:25]
	v_mfma_f32_16x16x32_bf16 v[22:25], v[186:189], v[222:225], v[22:25]
	v_mfma_f32_16x16x32_bf16 v[10:13], v[156:159], v[226:229], v[10:13]
	v_mfma_f32_16x16x32_bf16 v[10:13], v[160:163], v[230:233], v[10:13]
	v_mfma_f32_16x16x32_bf16 v[2:5], v[182:185], v[226:229], v[2:5]
	v_mfma_f32_16x16x32_bf16 v[2:5], v[186:189], v[230:233], v[2:5]
	s_setprio 0
	s_barrier
	s_cmp_gt_u32 s97, 13
	s_cbranch_scc0 .LBB0_488
	s_and_b64 vcc, exec, s[48:49]
	s_cbranch_vccz .LBB0_491
	s_barrier

.LBB0_604:
	s_add_i32 s22, 0, 0x10000
	s_add_i32 s23, 0, 0x14000
	v_add_u32_e32 v150, s22, v139
	v_add_u32_e32 v162, s23, v139
	ds_read_b128 v[134:137], v150
	ds_read_b128 v[142:145], v150 offset:1024
	ds_read_b128 v[146:149], v150 offset:2048
	ds_read_b128 v[150:153], v150 offset:3072
	ds_read_b128 v[154:157], v162
	ds_read_b128 v[158:161], v162 offset:1024
	ds_read_b128 v[182:185], v162 offset:2048
	ds_read_b128 v[186:189], v162 offset:3072
	ds_read_b128 v[190:193], v141
	ds_read_b128 v[194:197], v141 offset:1024
	ds_read_b128 v[198:201], v141 offset:2048
	ds_read_b128 v[214:217], v141 offset:3072
	ds_read_b128 v[218:221], v141 offset:4096
	ds_read_b128 v[222:225], v141 offset:5120
	ds_read_b128 v[226:229], v141 offset:6144
	ds_read_b128 v[230:233], v141 offset:7168
	s_add_u32 s20, s6, 0xfffe0080
	s_addc_u32 s21, s7, -1
	s_cmp_eq_u32 s84, 4
	s_cselect_b32 s69, s42, s21
	s_cselect_b32 s68, s43, s20
	s_cselect_b32 s21, s46, s51
	s_cselect_b32 s20, s47, s49
	v_lshl_add_u64 v[162:163], s[6:7], 0, v[132:133]
	s_add_i32 m0, s89, 0xc000
	s_nop 0
	global_load_lds_dwordx4 v[162:163], off
	v_lshl_add_u64 v[162:163], v[162:163], 0, s[64:65]
	s_add_i32 m0, s89, 0xe000
	s_nop 0
	global_load_lds_dwordx4 v[162:163], off
	s_waitcnt vmcnt(8)
	s_waitcnt lgkmcnt(0)
	s_barrier
	s_setprio 1
	s_waitcnt lgkmcnt(0)
	v_mfma_f32_16x16x32_bf16 v[126:129], v[134:137], v[190:193], v[126:129]
	v_mfma_f32_16x16x32_bf16 v[126:129], v[142:145], v[194:197], v[126:129]
	v_mfma_f32_16x16x32_bf16 v[122:125], v[146:149], v[190:193], v[122:125]
	v_mfma_f32_16x16x32_bf16 v[122:125], v[150:153], v[194:197], v[122:125]
	v_mfma_f32_16x16x32_bf16 v[110:113], v[134:137], v[198:201], v[110:113]
	v_mfma_f32_16x16x32_bf16 v[110:113], v[142:145], v[214:217], v[110:113]
	v_mfma_f32_16x16x32_bf16 v[106:109], v[146:149], v[198:201], v[106:109]
	v_mfma_f32_16x16x32_bf16 v[106:109], v[150:153], v[214:217], v[106:109]
	v_mfma_f32_16x16x32_bf16 v[94:97], v[134:137], v[218:221], v[94:97]
	v_mfma_f32_16x16x32_bf16 v[94:97], v[142:145], v[222:225], v[94:97]
	v_mfma_f32_16x16x32_bf16 v[90:93], v[146:149], v[218:221], v[90:93]
	v_mfma_f32_16x16x32_bf16 v[90:93], v[150:153], v[222:225], v[90:93]
	v_mfma_f32_16x16x32_bf16 v[78:81], v[134:137], v[226:229], v[78:81]
	v_mfma_f32_16x16x32_bf16 v[78:81], v[142:145], v[230:233], v[78:81]
	v_mfma_f32_16x16x32_bf16 v[74:77], v[146:149], v[226:229], v[74:77]
	v_mfma_f32_16x16x32_bf16 v[74:77], v[150:153], v[230:233], v[74:77]
	s_setprio 0
	s_setprio 1
	v_mfma_f32_16x16x32_bf16 v[118:121], v[154:157], v[190:193], v[118:121]
	v_mfma_f32_16x16x32_bf16 v[118:121], v[158:161], v[194:197], v[118:121]
	v_mfma_f32_16x16x32_bf16 v[114:117], v[182:185], v[190:193], v[114:117]
	v_mfma_f32_16x16x32_bf16 v[114:117], v[186:189], v[194:197], v[114:117]
	v_mfma_f32_16x16x32_bf16 v[102:105], v[154:157], v[198:201], v[102:105]
	v_mfma_f32_16x16x32_bf16 v[102:105], v[158:161], v[214:217], v[102:105]
	v_mfma_f32_16x16x32_bf16 v[98:101], v[182:185], v[198:201], v[98:101]
	v_mfma_f32_16x16x32_bf16 v[98:101], v[186:189], v[214:217], v[98:101]
	v_mfma_f32_16x16x32_bf16 v[86:89], v[154:157], v[218:221], v[86:89]
	v_mfma_f32_16x16x32_bf16 v[86:89], v[158:161], v[222:225], v[86:89]
	v_mfma_f32_16x16x32_bf16 v[82:85], v[182:185], v[218:221], v[82:85]
	v_mfma_f32_16x16x32_bf16 v[82:85], v[186:189], v[222:225], v[82:85]
	v_mfma_f32_16x16x32_bf16 v[70:73], v[154:157], v[226:229], v[70:73]
	v_mfma_f32_16x16x32_bf16 v[70:73], v[158:161], v[230:233], v[70:73]
	v_mfma_f32_16x16x32_bf16 v[66:69], v[182:185], v[226:229], v[66:69]
	v_mfma_f32_16x16x32_bf16 v[66:69], v[186:189], v[230:233], v[66:69]
	s_setprio 0
	s_barrier
	ds_read_b128 v[190:193], v141 offset:16384
	ds_read_b128 v[194:197], v141 offset:17408
	ds_read_b128 v[198:201], v141 offset:18432
	ds_read_b128 v[214:217], v141 offset:19456
	ds_read_b128 v[218:221], v141 offset:20480
	ds_read_b128 v[222:225], v141 offset:21504
	ds_read_b128 v[226:229], v141 offset:22528
	ds_read_b128 v[230:233], v141 offset:23552
	v_lshl_add_u64 v[162:163], s[20:21], 0, v[0:1]
	s_add_i32 s20, s22, s88
	s_mov_b32 m0, s20
	s_nop 0
	global_load_lds_dwordx4 v[162:163], off
	v_lshl_add_u64 v[202:203], v[162:163], 0, s[64:65]
	s_add_i32 m0, s20, 0x2000
	s_add_i32 s20, s23, s88
	global_load_lds_dwordx4 v[202:203], off
	v_lshl_add_u64 v[202:203], v[162:163], 0, s[72:73]
	s_mov_b32 m0, s20
	s_nop 0
	global_load_lds_dwordx4 v[202:203], off
	v_lshl_add_u64 v[202:203], v[162:163], 0, s[74:75]
	s_add_i32 m0, s20, 0x2000
	s_nop 0
	global_load_lds_dwordx4 v[202:203], off
	v_lshl_add_u64 v[202:203], s[68:69], 0, v[130:131]
	s_mov_b32 m0, s89
	v_lshl_add_u64 v[234:235], v[202:203], 0, s[64:65]
	global_load_lds_dwordx4 v[202:203], off
	s_mov_b32 m0, s90
	s_nop 0
	global_load_lds_dwordx4 v[234:235], off
	s_waitcnt vmcnt(8)
	s_waitcnt lgkmcnt(0)
	s_barrier
	s_setprio 1
	s_waitcnt lgkmcnt(0)
	v_mfma_f32_16x16x32_bf16 v[62:65], v[134:137], v[190:193], v[62:65]
	v_mfma_f32_16x16x32_bf16 v[62:65], v[142:145], v[194:197], v[62:65]
	v_mfma_f32_16x16x32_bf16 v[58:61], v[146:149], v[190:193], v[58:61]
	v_mfma_f32_16x16x32_bf16 v[58:61], v[150:153], v[194:197], v[58:61]
	v_mfma_f32_16x16x32_bf16 v[46:49], v[134:137], v[198:201], v[46:49]
	v_mfma_f32_16x16x32_bf16 v[46:49], v[142:145], v[214:217], v[46:49]
	v_mfma_f32_16x16x32_bf16 v[42:45], v[146:149], v[198:201], v[42:45]
	v_mfma_f32_16x16x32_bf16 v[42:45], v[150:153], v[214:217], v[42:45]
	v_mfma_f32_16x16x32_bf16 v[30:33], v[134:137], v[218:221], v[30:33]
	v_mfma_f32_16x16x32_bf16 v[30:33], v[142:145], v[222:225], v[30:33]
	v_mfma_f32_16x16x32_bf16 v[26:29], v[146:149], v[218:221], v[26:29]
	v_mfma_f32_16x16x32_bf16 v[26:29], v[150:153], v[222:225], v[26:29]
	v_mfma_f32_16x16x32_bf16 v[14:17], v[134:137], v[226:229], v[14:17]
	v_mfma_f32_16x16x32_bf16 v[14:17], v[142:145], v[230:233], v[14:17]
	v_mfma_f32_16x16x32_bf16 v[10:13], v[146:149], v[226:229], v[10:13]
	v_mfma_f32_16x16x32_bf16 v[10:13], v[150:153], v[230:233], v[10:13]
	s_setprio 0
	s_setprio 1
	v_mfma_f32_16x16x32_bf16 v[54:57], v[154:157], v[190:193], v[54:57]
	v_mfma_f32_16x16x32_bf16 v[54:57], v[158:161], v[194:197], v[54:57]
	v_mfma_f32_16x16x32_bf16 v[50:53], v[182:185], v[190:193], v[50:53]
	v_mfma_f32_16x16x32_bf16 v[50:53], v[186:189], v[194:197], v[50:53]
	v_mfma_f32_16x16x32_bf16 v[38:41], v[154:157], v[198:201], v[38:41]
	v_mfma_f32_16x16x32_bf16 v[38:41], v[158:161], v[214:217], v[38:41]
	v_mfma_f32_16x16x32_bf16 v[34:37], v[182:185], v[198:201], v[34:37]
	v_mfma_f32_16x16x32_bf16 v[34:37], v[186:189], v[214:217], v[34:37]
	v_mfma_f32_16x16x32_bf16 v[22:25], v[154:157], v[218:221], v[22:25]
	v_mfma_f32_16x16x32_bf16 v[22:25], v[158:161], v[222:225], v[22:25]
	v_mfma_f32_16x16x32_bf16 v[18:21], v[182:185], v[218:221], v[18:21]
	v_mfma_f32_16x16x32_bf16 v[18:21], v[186:189], v[222:225], v[18:21]
	v_mfma_f32_16x16x32_bf16 v[6:9], v[154:157], v[226:229], v[6:9]
	v_mfma_f32_16x16x32_bf16 v[6:9], v[158:161], v[230:233], v[6:9]
	v_mfma_f32_16x16x32_bf16 v[2:5], v[182:185], v[226:229], v[2:5]
	v_mfma_f32_16x16x32_bf16 v[2:5], v[186:189], v[230:233], v[2:5]
	s_setprio 0
	s_barrier
	s_add_i32 s20, 0, 0x18000
	s_add_i32 s21, 0, 0x1c000
	v_add_u32_e32 v150, s20, v139
	v_add_u32_e32 v186, s21, v139
	ds_read_b128 v[134:137], v150
	ds_read_b128 v[142:145], v150 offset:1024
	ds_read_b128 v[146:149], v150 offset:2048
	ds_read_b128 v[150:153], v150 offset:3072
	ds_read_b128 v[154:157], v186
	ds_read_b128 v[158:161], v186 offset:1024
	ds_read_b128 v[182:185], v186 offset:2048
	ds_read_b128 v[186:189], v186 offset:3072
	ds_read_b128 v[190:193], v141 offset:32768
	ds_read_b128 v[194:197], v141 offset:33792
	ds_read_b128 v[198:201], v141 offset:34816
	ds_read_b128 v[214:217], v141 offset:35840
	ds_read_b128 v[218:221], v141 offset:36864
	ds_read_b128 v[222:225], v141 offset:37888
	ds_read_b128 v[226:229], v141 offset:38912
	ds_read_b128 v[230:233], v141 offset:39936
	s_mov_b32 m0, s91
	v_lshl_add_u64 v[234:235], v[202:203], 0, s[72:73]
	global_load_lds_dwordx4 v[234:235], off
	v_lshl_add_u64 v[234:235], v[202:203], 0, s[74:75]
	s_mov_b32 m0, s96
	s_nop 0
	global_load_lds_dwordx4 v[234:235], off
	s_waitcnt vmcnt(8)
	s_waitcnt lgkmcnt(0)
	s_barrier
	s_setprio 1
	s_waitcnt lgkmcnt(0)
	v_mfma_f32_16x16x32_bf16 v[126:129], v[134:137], v[190:193], v[126:129]
	v_mfma_f32_16x16x32_bf16 v[126:129], v[142:145], v[194:197], v[126:129]
	v_mfma_f32_16x16x32_bf16 v[122:125], v[146:149], v[190:193], v[122:125]
	v_mfma_f32_16x16x32_bf16 v[122:125], v[150:153], v[194:197], v[122:125]
	v_mfma_f32_16x16x32_bf16 v[110:113], v[134:137], v[198:201], v[110:113]
	v_mfma_f32_16x16x32_bf16 v[110:113], v[142:145], v[214:217], v[110:113]
	v_mfma_f32_16x16x32_bf16 v[106:109], v[146:149], v[198:201], v[106:109]
	v_mfma_f32_16x16x32_bf16 v[106:109], v[150:153], v[214:217], v[106:109]
	v_mfma_f32_16x16x32_bf16 v[94:97], v[134:137], v[218:221], v[94:97]
	v_mfma_f32_16x16x32_bf16 v[94:97], v[142:145], v[222:225], v[94:97]
	v_mfma_f32_16x16x32_bf16 v[90:93], v[146:149], v[218:221], v[90:93]
	v_mfma_f32_16x16x32_bf16 v[90:93], v[150:153], v[222:225], v[90:93]
	v_mfma_f32_16x16x32_bf16 v[78:81], v[134:137], v[226:229], v[78:81]
	v_mfma_f32_16x16x32_bf16 v[78:81], v[142:145], v[230:233], v[78:81]
	v_mfma_f32_16x16x32_bf16 v[74:77], v[146:149], v[226:229], v[74:77]
	v_mfma_f32_16x16x32_bf16 v[74:77], v[150:153], v[230:233], v[74:77]
	s_setprio 0
	s_setprio 1
	v_mfma_f32_16x16x32_bf16 v[118:121], v[154:157], v[190:193], v[118:121]
	v_mfma_f32_16x16x32_bf16 v[118:121], v[158:161], v[194:197], v[118:121]
	v_mfma_f32_16x16x32_bf16 v[114:117], v[182:185], v[190:193], v[114:117]
	v_mfma_f32_16x16x32_bf16 v[114:117], v[186:189], v[194:197], v[114:117]
	v_mfma_f32_16x16x32_bf16 v[102:105], v[154:157], v[198:201], v[102:105]
	v_mfma_f32_16x16x32_bf16 v[102:105], v[158:161], v[214:217], v[102:105]
	v_mfma_f32_16x16x32_bf16 v[98:101], v[182:185], v[198:201], v[98:101]
	v_mfma_f32_16x16x32_bf16 v[98:101], v[186:189], v[214:217], v[98:101]
	v_mfma_f32_16x16x32_bf16 v[86:89], v[154:157], v[218:221], v[86:89]
	v_mfma_f32_16x16x32_bf16 v[86:89], v[158:161], v[222:225], v[86:89]
	v_mfma_f32_16x16x32_bf16 v[82:85], v[182:185], v[218:221], v[82:85]
	v_mfma_f32_16x16x32_bf16 v[82:85], v[186:189], v[222:225], v[82:85]
	v_mfma_f32_16x16x32_bf16 v[70:73], v[154:157], v[226:229], v[70:73]
	v_mfma_f32_16x16x32_bf16 v[70:73], v[158:161], v[230:233], v[70:73]
	v_mfma_f32_16x16x32_bf16 v[66:69], v[182:185], v[226:229], v[66:69]
	v_mfma_f32_16x16x32_bf16 v[66:69], v[186:189], v[230:233], v[66:69]
	s_setprio 0
	s_barrier
	ds_read_b128 v[190:193], v141 offset:49152
	ds_read_b128 v[194:197], v141 offset:50176
	ds_read_b128 v[198:201], v141 offset:51200
	ds_read_b128 v[214:217], v141 offset:52224
	ds_read_b128 v[218:221], v141 offset:53248
	ds_read_b128 v[222:225], v141 offset:54272
	ds_read_b128 v[226:229], v141 offset:55296
	ds_read_b128 v[230:233], v141 offset:56320
	s_add_i32 s20, s20, s88
	v_lshl_add_u64 v[234:235], v[162:163], 0, s[34:35]
	s_mov_b32 m0, s20
	s_nop 0
	global_load_lds_dwordx4 v[234:235], off
	v_lshl_add_u64 v[234:235], v[162:163], 0, s[80:81]
	s_add_i32 m0, s20, 0x2000
	s_add_i32 s20, s21, s88
	global_load_lds_dwordx4 v[234:235], off
	v_lshl_add_u64 v[234:235], v[162:163], 0, s[38:39]
	s_mov_b32 m0, s20
	v_lshl_add_u64 v[162:163], v[162:163], 0, s[86:87]
	global_load_lds_dwordx4 v[234:235], off
	s_add_i32 m0, s20, 0x2000
	s_nop 0
	global_load_lds_dwordx4 v[162:163], off
	v_lshl_add_u64 v[162:163], v[202:203], 0, s[34:35]
	s_mov_b32 m0, s97
	s_nop 0
	global_load_lds_dwordx4 v[162:163], off
	v_lshl_add_u64 v[162:163], v[202:203], 0, s[80:81]
	s_mov_b32 m0, s58
	s_nop 0
	global_load_lds_dwordx4 v[162:163], off
	s_waitcnt vmcnt(8)
	s_waitcnt lgkmcnt(0)
	s_barrier
	s_setprio 1
	s_waitcnt lgkmcnt(0)
	v_mfma_f32_16x16x32_bf16 v[62:65], v[134:137], v[190:193], v[62:65]
	v_mfma_f32_16x16x32_bf16 v[62:65], v[142:145], v[194:197], v[62:65]
	v_mfma_f32_16x16x32_bf16 v[58:61], v[146:149], v[190:193], v[58:61]
	v_mfma_f32_16x16x32_bf16 v[58:61], v[150:153], v[194:197], v[58:61]
	v_mfma_f32_16x16x32_bf16 v[46:49], v[134:137], v[198:201], v[46:49]
	v_mfma_f32_16x16x32_bf16 v[46:49], v[142:145], v[214:217], v[46:49]
	v_mfma_f32_16x16x32_bf16 v[42:45], v[146:149], v[198:201], v[42:45]
	v_mfma_f32_16x16x32_bf16 v[42:45], v[150:153], v[214:217], v[42:45]
	v_mfma_f32_16x16x32_bf16 v[30:33], v[134:137], v[218:221], v[30:33]
	v_mfma_f32_16x16x32_bf16 v[30:33], v[142:145], v[222:225], v[30:33]
	v_mfma_f32_16x16x32_bf16 v[26:29], v[146:149], v[218:221], v[26:29]
	v_mfma_f32_16x16x32_bf16 v[26:29], v[150:153], v[222:225], v[26:29]
	v_mfma_f32_16x16x32_bf16 v[14:17], v[134:137], v[226:229], v[14:17]
	v_mfma_f32_16x16x32_bf16 v[14:17], v[142:145], v[230:233], v[14:17]
	v_mfma_f32_16x16x32_bf16 v[10:13], v[146:149], v[226:229], v[10:13]
	v_mfma_f32_16x16x32_bf16 v[10:13], v[150:153], v[230:233], v[10:13]
	s_add_i32 s84, s84, 2
	s_add_u32 s6, s6, 0x100
	s_addc_u32 s7, s7, 0
	s_add_u32 s49, s49, 0x100
	s_addc_u32 s51, s51, 0
	s_setprio 0
	s_setprio 1
	v_mfma_f32_16x16x32_bf16 v[54:57], v[154:157], v[190:193], v[54:57]
	v_mfma_f32_16x16x32_bf16 v[54:57], v[158:161], v[194:197], v[54:57]
	v_mfma_f32_16x16x32_bf16 v[50:53], v[182:185], v[190:193], v[50:53]
	v_mfma_f32_16x16x32_bf16 v[50:53], v[186:189], v[194:197], v[50:53]
	v_mfma_f32_16x16x32_bf16 v[38:41], v[154:157], v[198:201], v[38:41]
	v_mfma_f32_16x16x32_bf16 v[38:41], v[158:161], v[214:217], v[38:41]
	v_mfma_f32_16x16x32_bf16 v[34:37], v[182:185], v[198:201], v[34:37]
	v_mfma_f32_16x16x32_bf16 v[34:37], v[186:189], v[214:217], v[34:37]
	v_mfma_f32_16x16x32_bf16 v[22:25], v[154:157], v[218:221], v[22:25]
	v_mfma_f32_16x16x32_bf16 v[22:25], v[158:161], v[222:225], v[22:25]
	v_mfma_f32_16x16x32_bf16 v[18:21], v[182:185], v[218:221], v[18:21]
	v_mfma_f32_16x16x32_bf16 v[18:21], v[186:189], v[222:225], v[18:21]
	v_mfma_f32_16x16x32_bf16 v[6:9], v[154:157], v[226:229], v[6:9]
	v_mfma_f32_16x16x32_bf16 v[6:9], v[158:161], v[230:233], v[6:9]
	v_mfma_f32_16x16x32_bf16 v[2:5], v[182:185], v[226:229], v[2:5]
	v_mfma_f32_16x16x32_bf16 v[2:5], v[186:189], v[230:233], v[2:5]
	s_setprio 0
	s_barrier
	s_cmp_gt_u32 s84, 5
	s_cbranch_scc0 .LBB0_604
	s_and_b64 vcc, exec, s[52:53]
	s_cbranch_vccz .LBB0_607
	s_barrier

.LBB0_778:
	s_add_i32 s22, 0, 0x10000
	s_add_i32 s23, 0, 0x14000
	v_add_u32_e32 v142, s22, v193
	v_add_u32_e32 v158, s23, v193
	ds_read_b128 v[130:133], v142
	ds_read_b128 v[134:137], v142 offset:1024
	ds_read_b128 v[138:141], v142 offset:2048
	ds_read_b128 v[142:145], v142 offset:3072
	ds_read_b128 v[146:149], v158
	ds_read_b128 v[150:153], v158 offset:1024
	ds_read_b128 v[154:157], v158 offset:2048
	ds_read_b128 v[158:161], v158 offset:3072
	ds_read_b128 v[184:187], v196
	ds_read_b128 v[188:191], v196 offset:1024
	ds_read_b128 v[198:201], v196 offset:2048
	ds_read_b128 v[214:217], v196 offset:3072
	ds_read_b128 v[218:221], v196 offset:4096
	ds_read_b128 v[222:225], v196 offset:5120
	ds_read_b128 v[226:229], v196 offset:6144
	ds_read_b128 v[230:233], v196 offset:7168
	s_add_u32 s20, s76, 0xfffc0080
	s_addc_u32 s21, s77, -1
	s_cmp_eq_u32 vcc_hi, 12
	s_cselect_b32 s79, s61, s21
	s_cselect_b32 s78, s85, s20
	s_cselect_b32 s21, s59, vcc_lo
	s_cselect_b32 s20, s86, s87
	v_lshl_add_u64 v[202:203], s[76:77], 0, v[182:183]
	s_add_i32 m0, s43, 0xc000
	s_nop 0
	global_load_lds_dwordx4 v[202:203], off
	v_lshl_add_u64 v[202:203], v[202:203], 0, s[72:73]
	s_add_i32 m0, s43, 0xe000
	s_nop 0
	global_load_lds_dwordx4 v[202:203], off
	s_waitcnt vmcnt(8)
	s_waitcnt lgkmcnt(0)
	s_barrier
	s_setprio 1
	s_waitcnt lgkmcnt(0)
	v_mfma_f32_16x16x32_bf16 v[126:129], v[130:133], v[184:187], v[126:129]
	v_mfma_f32_16x16x32_bf16 v[126:129], v[134:137], v[188:191], v[126:129]
	v_mfma_f32_16x16x32_bf16 v[122:125], v[138:141], v[184:187], v[122:125]
	v_mfma_f32_16x16x32_bf16 v[122:125], v[142:145], v[188:191], v[122:125]
	v_mfma_f32_16x16x32_bf16 v[110:113], v[130:133], v[198:201], v[110:113]
	v_mfma_f32_16x16x32_bf16 v[110:113], v[134:137], v[214:217], v[110:113]
	v_mfma_f32_16x16x32_bf16 v[106:109], v[138:141], v[198:201], v[106:109]
	v_mfma_f32_16x16x32_bf16 v[106:109], v[142:145], v[214:217], v[106:109]
	v_mfma_f32_16x16x32_bf16 v[94:97], v[130:133], v[218:221], v[94:97]
	v_mfma_f32_16x16x32_bf16 v[94:97], v[134:137], v[222:225], v[94:97]
	v_mfma_f32_16x16x32_bf16 v[90:93], v[138:141], v[218:221], v[90:93]
	v_mfma_f32_16x16x32_bf16 v[90:93], v[142:145], v[222:225], v[90:93]
	v_mfma_f32_16x16x32_bf16 v[78:81], v[130:133], v[226:229], v[78:81]
	v_mfma_f32_16x16x32_bf16 v[78:81], v[134:137], v[230:233], v[78:81]
	v_mfma_f32_16x16x32_bf16 v[74:77], v[138:141], v[226:229], v[74:77]
	v_mfma_f32_16x16x32_bf16 v[74:77], v[142:145], v[230:233], v[74:77]
	s_setprio 0
	s_setprio 1
	v_mfma_f32_16x16x32_bf16 v[118:121], v[146:149], v[184:187], v[118:121]
	v_mfma_f32_16x16x32_bf16 v[118:121], v[150:153], v[188:191], v[118:121]
	v_mfma_f32_16x16x32_bf16 v[114:117], v[154:157], v[184:187], v[114:117]
	v_mfma_f32_16x16x32_bf16 v[114:117], v[158:161], v[188:191], v[114:117]
	v_mfma_f32_16x16x32_bf16 v[102:105], v[146:149], v[198:201], v[102:105]
	v_mfma_f32_16x16x32_bf16 v[102:105], v[150:153], v[214:217], v[102:105]
	v_mfma_f32_16x16x32_bf16 v[98:101], v[154:157], v[198:201], v[98:101]
	v_mfma_f32_16x16x32_bf16 v[98:101], v[158:161], v[214:217], v[98:101]
	v_mfma_f32_16x16x32_bf16 v[86:89], v[146:149], v[218:221], v[86:89]
	v_mfma_f32_16x16x32_bf16 v[86:89], v[150:153], v[222:225], v[86:89]
	v_mfma_f32_16x16x32_bf16 v[82:85], v[154:157], v[218:221], v[82:85]
	v_mfma_f32_16x16x32_bf16 v[82:85], v[158:161], v[222:225], v[82:85]
	v_mfma_f32_16x16x32_bf16 v[70:73], v[146:149], v[226:229], v[70:73]
	v_mfma_f32_16x16x32_bf16 v[70:73], v[150:153], v[230:233], v[70:73]
	v_mfma_f32_16x16x32_bf16 v[66:69], v[154:157], v[226:229], v[66:69]
	v_mfma_f32_16x16x32_bf16 v[66:69], v[158:161], v[230:233], v[66:69]
	s_setprio 0
	s_barrier
	ds_read_b128 v[184:187], v196 offset:16384
	ds_read_b128 v[188:191], v196 offset:17408
	ds_read_b128 v[198:201], v196 offset:18432
	ds_read_b128 v[214:217], v196 offset:19456
	ds_read_b128 v[218:221], v196 offset:20480
	ds_read_b128 v[222:225], v196 offset:21504
	ds_read_b128 v[226:229], v196 offset:22528
	ds_read_b128 v[230:233], v196 offset:23552
	v_lshl_add_u64 v[202:203], s[20:21], 0, v[0:1]
	s_add_i32 s20, s22, s14
	s_mov_b32 m0, s20
	s_nop 0
	global_load_lds_dwordx4 v[202:203], off
	v_lshl_add_u64 v[234:235], v[202:203], 0, s[72:73]
	s_add_i32 m0, s20, 0x2000
	s_add_i32 s20, s23, s14
	global_load_lds_dwordx4 v[234:235], off
	v_lshl_add_u64 v[234:235], v[202:203], 0, s[28:29]
	s_mov_b32 m0, s20
	s_nop 0
	global_load_lds_dwordx4 v[234:235], off
	v_lshl_add_u64 v[234:235], v[202:203], 0, s[82:83]
	s_add_i32 m0, s20, 0x2000
	s_nop 0
	global_load_lds_dwordx4 v[234:235], off
	v_lshl_add_u64 v[234:235], s[78:79], 0, v[162:163]
	s_mov_b32 m0, s43
	v_lshl_add_u64 v[236:237], v[234:235], 0, s[72:73]
	global_load_lds_dwordx4 v[234:235], off
	s_mov_b32 m0, s46
	s_nop 0
	global_load_lds_dwordx4 v[236:237], off
	s_waitcnt vmcnt(8)
	s_waitcnt lgkmcnt(0)
	s_barrier
	s_setprio 1
	s_waitcnt lgkmcnt(0)
	v_mfma_f32_16x16x32_bf16 v[62:65], v[130:133], v[184:187], v[62:65]
	v_mfma_f32_16x16x32_bf16 v[62:65], v[134:137], v[188:191], v[62:65]
	v_mfma_f32_16x16x32_bf16 v[58:61], v[138:141], v[184:187], v[58:61]
	v_mfma_f32_16x16x32_bf16 v[58:61], v[142:145], v[188:191], v[58:61]
	v_mfma_f32_16x16x32_bf16 v[46:49], v[130:133], v[198:201], v[46:49]
	v_mfma_f32_16x16x32_bf16 v[46:49], v[134:137], v[214:217], v[46:49]
	v_mfma_f32_16x16x32_bf16 v[42:45], v[138:141], v[198:201], v[42:45]
	v_mfma_f32_16x16x32_bf16 v[42:45], v[142:145], v[214:217], v[42:45]
	v_mfma_f32_16x16x32_bf16 v[30:33], v[130:133], v[218:221], v[30:33]
	v_mfma_f32_16x16x32_bf16 v[30:33], v[134:137], v[222:225], v[30:33]
	v_mfma_f32_16x16x32_bf16 v[26:29], v[138:141], v[218:221], v[26:29]
	v_mfma_f32_16x16x32_bf16 v[26:29], v[142:145], v[222:225], v[26:29]
	v_mfma_f32_16x16x32_bf16 v[14:17], v[130:133], v[226:229], v[14:17]
	v_mfma_f32_16x16x32_bf16 v[14:17], v[134:137], v[230:233], v[14:17]
	v_mfma_f32_16x16x32_bf16 v[10:13], v[138:141], v[226:229], v[10:13]
	v_mfma_f32_16x16x32_bf16 v[10:13], v[142:145], v[230:233], v[10:13]
	s_setprio 0
	s_setprio 1
	v_mfma_f32_16x16x32_bf16 v[54:57], v[146:149], v[184:187], v[54:57]
	v_mfma_f32_16x16x32_bf16 v[54:57], v[150:153], v[188:191], v[54:57]
	v_mfma_f32_16x16x32_bf16 v[50:53], v[154:157], v[184:187], v[50:53]
	v_mfma_f32_16x16x32_bf16 v[50:53], v[158:161], v[188:191], v[50:53]
	v_mfma_f32_16x16x32_bf16 v[38:41], v[146:149], v[198:201], v[38:41]
	v_mfma_f32_16x16x32_bf16 v[38:41], v[150:153], v[214:217], v[38:41]
	v_mfma_f32_16x16x32_bf16 v[34:37], v[154:157], v[198:201], v[34:37]
	v_mfma_f32_16x16x32_bf16 v[34:37], v[158:161], v[214:217], v[34:37]
	v_mfma_f32_16x16x32_bf16 v[22:25], v[146:149], v[218:221], v[22:25]
	v_mfma_f32_16x16x32_bf16 v[22:25], v[150:153], v[222:225], v[22:25]
	v_mfma_f32_16x16x32_bf16 v[18:21], v[154:157], v[218:221], v[18:21]
	v_mfma_f32_16x16x32_bf16 v[18:21], v[158:161], v[222:225], v[18:21]
	v_mfma_f32_16x16x32_bf16 v[6:9], v[146:149], v[226:229], v[6:9]
	v_mfma_f32_16x16x32_bf16 v[6:9], v[150:153], v[230:233], v[6:9]
	v_mfma_f32_16x16x32_bf16 v[2:5], v[154:157], v[226:229], v[2:5]
	v_mfma_f32_16x16x32_bf16 v[2:5], v[158:161], v[230:233], v[2:5]
	s_setprio 0
	s_barrier
	s_add_i32 s20, 0, 0x18000
	s_add_i32 s21, 0, 0x1c000
	v_add_u32_e32 v142, s20, v193
	v_add_u32_e32 v158, s21, v193
	ds_read_b128 v[130:133], v142
	ds_read_b128 v[134:137], v142 offset:1024
	ds_read_b128 v[138:141], v142 offset:2048
	ds_read_b128 v[142:145], v142 offset:3072
	ds_read_b128 v[146:149], v158
	ds_read_b128 v[150:153], v158 offset:1024
	ds_read_b128 v[154:157], v158 offset:2048
	ds_read_b128 v[158:161], v158 offset:3072
	ds_read_b128 v[184:187], v196 offset:32768
	ds_read_b128 v[188:191], v196 offset:33792
	ds_read_b128 v[198:201], v196 offset:34816
	ds_read_b128 v[214:217], v196 offset:35840
	ds_read_b128 v[218:221], v196 offset:36864
	ds_read_b128 v[222:225], v196 offset:37888
	ds_read_b128 v[226:229], v196 offset:38912
	ds_read_b128 v[230:233], v196 offset:39936
	s_mov_b32 m0, s47
	v_lshl_add_u64 v[236:237], v[234:235], 0, s[28:29]
	global_load_lds_dwordx4 v[236:237], off
	v_lshl_add_u64 v[236:237], v[234:235], 0, s[82:83]
	s_mov_b32 m0, s88
	s_nop 0
	global_load_lds_dwordx4 v[236:237], off
	s_waitcnt vmcnt(8)
	s_waitcnt lgkmcnt(0)
	s_barrier
	s_setprio 1
	s_waitcnt lgkmcnt(0)
	v_mfma_f32_16x16x32_bf16 v[126:129], v[130:133], v[184:187], v[126:129]
	v_mfma_f32_16x16x32_bf16 v[126:129], v[134:137], v[188:191], v[126:129]
	v_mfma_f32_16x16x32_bf16 v[122:125], v[138:141], v[184:187], v[122:125]
	v_mfma_f32_16x16x32_bf16 v[122:125], v[142:145], v[188:191], v[122:125]
	v_mfma_f32_16x16x32_bf16 v[110:113], v[130:133], v[198:201], v[110:113]
	v_mfma_f32_16x16x32_bf16 v[110:113], v[134:137], v[214:217], v[110:113]
	v_mfma_f32_16x16x32_bf16 v[106:109], v[138:141], v[198:201], v[106:109]
	v_mfma_f32_16x16x32_bf16 v[106:109], v[142:145], v[214:217], v[106:109]
	v_mfma_f32_16x16x32_bf16 v[94:97], v[130:133], v[218:221], v[94:97]
	v_mfma_f32_16x16x32_bf16 v[94:97], v[134:137], v[222:225], v[94:97]
	v_mfma_f32_16x16x32_bf16 v[90:93], v[138:141], v[218:221], v[90:93]
	v_mfma_f32_16x16x32_bf16 v[90:93], v[142:145], v[222:225], v[90:93]
	v_mfma_f32_16x16x32_bf16 v[78:81], v[130:133], v[226:229], v[78:81]
	v_mfma_f32_16x16x32_bf16 v[78:81], v[134:137], v[230:233], v[78:81]
	v_mfma_f32_16x16x32_bf16 v[74:77], v[138:141], v[226:229], v[74:77]
	v_mfma_f32_16x16x32_bf16 v[74:77], v[142:145], v[230:233], v[74:77]
	s_setprio 0
	s_setprio 1
	v_mfma_f32_16x16x32_bf16 v[118:121], v[146:149], v[184:187], v[118:121]
	v_mfma_f32_16x16x32_bf16 v[118:121], v[150:153], v[188:191], v[118:121]
	v_mfma_f32_16x16x32_bf16 v[114:117], v[154:157], v[184:187], v[114:117]
	v_mfma_f32_16x16x32_bf16 v[114:117], v[158:161], v[188:191], v[114:117]
	v_mfma_f32_16x16x32_bf16 v[102:105], v[146:149], v[198:201], v[102:105]
	v_mfma_f32_16x16x32_bf16 v[102:105], v[150:153], v[214:217], v[102:105]
	v_mfma_f32_16x16x32_bf16 v[98:101], v[154:157], v[198:201], v[98:101]
	v_mfma_f32_16x16x32_bf16 v[98:101], v[158:161], v[214:217], v[98:101]
	v_mfma_f32_16x16x32_bf16 v[86:89], v[146:149], v[218:221], v[86:89]
	v_mfma_f32_16x16x32_bf16 v[86:89], v[150:153], v[222:225], v[86:89]
	v_mfma_f32_16x16x32_bf16 v[82:85], v[154:157], v[218:221], v[82:85]
	v_mfma_f32_16x16x32_bf16 v[82:85], v[158:161], v[222:225], v[82:85]
	v_mfma_f32_16x16x32_bf16 v[70:73], v[146:149], v[226:229], v[70:73]
	v_mfma_f32_16x16x32_bf16 v[70:73], v[150:153], v[230:233], v[70:73]
	v_mfma_f32_16x16x32_bf16 v[66:69], v[154:157], v[226:229], v[66:69]
	v_mfma_f32_16x16x32_bf16 v[66:69], v[158:161], v[230:233], v[66:69]
	s_setprio 0
	s_barrier
	ds_read_b128 v[184:187], v196 offset:49152
	ds_read_b128 v[188:191], v196 offset:50176
	ds_read_b128 v[198:201], v196 offset:51200
	ds_read_b128 v[214:217], v196 offset:52224
	ds_read_b128 v[218:221], v196 offset:53248
	ds_read_b128 v[222:225], v196 offset:54272
	ds_read_b128 v[226:229], v196 offset:55296
	ds_read_b128 v[230:233], v196 offset:56320
	s_add_i32 s20, s20, s14
	v_lshl_add_u64 v[236:237], v[202:203], 0, s[34:35]
	s_mov_b32 m0, s20
	s_nop 0
	global_load_lds_dwordx4 v[236:237], off
	v_lshl_add_u64 v[236:237], v[202:203], 0, s[38:39]
	s_add_i32 m0, s20, 0x2000
	s_add_i32 s20, s21, s14
	global_load_lds_dwordx4 v[236:237], off
	v_lshl_add_u64 v[236:237], v[202:203], 0, s[44:45]
	s_mov_b32 m0, s20
	v_lshl_add_u64 v[202:203], v[202:203], 0, s[10:11]
	global_load_lds_dwordx4 v[236:237], off
	s_add_i32 m0, s20, 0x2000
	s_nop 0
	global_load_lds_dwordx4 v[202:203], off
	v_lshl_add_u64 v[202:203], v[234:235], 0, s[34:35]
	s_mov_b32 m0, s89
	s_nop 0
	global_load_lds_dwordx4 v[202:203], off
	v_lshl_add_u64 v[202:203], v[234:235], 0, s[38:39]
	s_mov_b32 m0, s90
	s_nop 0
	global_load_lds_dwordx4 v[202:203], off
	s_waitcnt vmcnt(8)
	s_waitcnt lgkmcnt(0)
	s_barrier
	s_setprio 1
	s_waitcnt lgkmcnt(0)
	v_mfma_f32_16x16x32_bf16 v[62:65], v[130:133], v[184:187], v[62:65]
	v_mfma_f32_16x16x32_bf16 v[62:65], v[134:137], v[188:191], v[62:65]
	v_mfma_f32_16x16x32_bf16 v[58:61], v[138:141], v[184:187], v[58:61]
	v_mfma_f32_16x16x32_bf16 v[58:61], v[142:145], v[188:191], v[58:61]
	v_mfma_f32_16x16x32_bf16 v[46:49], v[130:133], v[198:201], v[46:49]
	v_mfma_f32_16x16x32_bf16 v[46:49], v[134:137], v[214:217], v[46:49]
	v_mfma_f32_16x16x32_bf16 v[42:45], v[138:141], v[198:201], v[42:45]
	v_mfma_f32_16x16x32_bf16 v[42:45], v[142:145], v[214:217], v[42:45]
	v_mfma_f32_16x16x32_bf16 v[30:33], v[130:133], v[218:221], v[30:33]
	v_mfma_f32_16x16x32_bf16 v[30:33], v[134:137], v[222:225], v[30:33]
	v_mfma_f32_16x16x32_bf16 v[26:29], v[138:141], v[218:221], v[26:29]
	v_mfma_f32_16x16x32_bf16 v[26:29], v[142:145], v[222:225], v[26:29]
	v_mfma_f32_16x16x32_bf16 v[14:17], v[130:133], v[226:229], v[14:17]
	v_mfma_f32_16x16x32_bf16 v[14:17], v[134:137], v[230:233], v[14:17]
	v_mfma_f32_16x16x32_bf16 v[10:13], v[138:141], v[226:229], v[10:13]
	v_mfma_f32_16x16x32_bf16 v[10:13], v[142:145], v[230:233], v[10:13]
	s_add_i32 vcc_hi, vcc_hi, 2
	s_add_u32 s76, s76, 0x100
	s_addc_u32 s77, s77, 0
	s_add_u32 s87, s87, 0x100
	s_addc_u32 vcc_lo, vcc_lo, 0
	s_setprio 0
	s_setprio 1
	v_mfma_f32_16x16x32_bf16 v[54:57], v[146:149], v[184:187], v[54:57]
	v_mfma_f32_16x16x32_bf16 v[54:57], v[150:153], v[188:191], v[54:57]
	v_mfma_f32_16x16x32_bf16 v[50:53], v[154:157], v[184:187], v[50:53]
	v_mfma_f32_16x16x32_bf16 v[50:53], v[158:161], v[188:191], v[50:53]
	v_mfma_f32_16x16x32_bf16 v[38:41], v[146:149], v[198:201], v[38:41]
	v_mfma_f32_16x16x32_bf16 v[38:41], v[150:153], v[214:217], v[38:41]
	v_mfma_f32_16x16x32_bf16 v[34:37], v[154:157], v[198:201], v[34:37]
	v_mfma_f32_16x16x32_bf16 v[34:37], v[158:161], v[214:217], v[34:37]
	v_mfma_f32_16x16x32_bf16 v[22:25], v[146:149], v[218:221], v[22:25]
	v_mfma_f32_16x16x32_bf16 v[22:25], v[150:153], v[222:225], v[22:25]
	v_mfma_f32_16x16x32_bf16 v[18:21], v[154:157], v[218:221], v[18:21]
	v_mfma_f32_16x16x32_bf16 v[18:21], v[158:161], v[222:225], v[18:21]
	v_mfma_f32_16x16x32_bf16 v[6:9], v[146:149], v[226:229], v[6:9]
	v_mfma_f32_16x16x32_bf16 v[6:9], v[150:153], v[230:233], v[6:9]
	v_mfma_f32_16x16x32_bf16 v[2:5], v[154:157], v[226:229], v[2:5]
	v_mfma_f32_16x16x32_bf16 v[2:5], v[158:161], v[230:233], v[2:5]
	s_setprio 0
	s_barrier
	s_cmp_gt_u32 vcc_hi, 13
	s_cbranch_scc0 .LBB0_778
	s_and_b64 vcc, exec, s[50:51]
	s_cbranch_vccz .LBB0_781
	s_barrier

.LBB0_850:
	s_add_i32 vcc_lo, 0, 0x10000
	v_add_u32_e32 v0, vcc_lo, v145
	s_add_i32 vcc_hi, 0, 0x14000
	ds_read_b128 v[138:141], v0
	ds_read_b128 v[146:149], v0 offset:1024
	ds_read_b128 v[150:153], v0 offset:2048
	ds_read_b128 v[158:161], v0 offset:3072
	v_add_u32_e32 v0, vcc_hi, v145
	ds_read_b128 v[182:185], v0
	ds_read_b128 v[186:189], v0 offset:1024
	ds_read_b128 v[190:193], v0 offset:2048
	ds_read_b128 v[194:197], v0 offset:3072
	ds_read_b128 v[198:201], v157
	ds_read_b128 v[214:217], v157 offset:1024
	ds_read_b128 v[218:221], v157 offset:2048
	ds_read_b128 v[222:225], v157 offset:3072
	ds_read_b128 v[226:229], v157 offset:4096
	ds_read_b128 v[230:233], v157 offset:5120
	ds_read_b128 v[234:237], v157 offset:6144
	ds_read_b128 v[238:241], v157 offset:7168
	s_add_u32 s20, s56, 0xfffc0080
	s_addc_u32 s21, s57, -1
	s_cmp_eq_u32 s91, 12
	s_cselect_b32 s59, s76, s21
	s_cselect_b32 s58, s77, s20
	s_cselect_b32 s21, s69, s87
	s_cselect_b32 s20, s79, s86
	v_lshl_add_u64 v[142:143], s[56:57], 0, v[136:137]
	s_add_i32 m0, s15, 0xc000
	s_nop 0
	global_load_lds_dwordx4 v[142:143], off
	v_lshl_add_u64 v[142:143], v[142:143], 0, s[72:73]
	s_add_i32 m0, s15, 0xe000
	s_nop 0
	global_load_lds_dwordx4 v[142:143], off
	s_waitcnt vmcnt(8)
	s_waitcnt lgkmcnt(0)
	s_barrier
	s_setprio 1
	s_waitcnt lgkmcnt(0)
	v_mfma_f32_16x16x32_bf16 v[126:129], v[138:141], v[198:201], v[126:129]
	v_mfma_f32_16x16x32_bf16 v[126:129], v[146:149], v[214:217], v[126:129]
	v_mfma_f32_16x16x32_bf16 v[122:125], v[150:153], v[198:201], v[122:125]
	v_mfma_f32_16x16x32_bf16 v[122:125], v[158:161], v[214:217], v[122:125]
	v_mfma_f32_16x16x32_bf16 v[110:113], v[138:141], v[218:221], v[110:113]
	v_mfma_f32_16x16x32_bf16 v[110:113], v[146:149], v[222:225], v[110:113]
	v_mfma_f32_16x16x32_bf16 v[106:109], v[150:153], v[218:221], v[106:109]
	v_mfma_f32_16x16x32_bf16 v[106:109], v[158:161], v[222:225], v[106:109]
	v_mfma_f32_16x16x32_bf16 v[94:97], v[138:141], v[226:229], v[94:97]
	v_mfma_f32_16x16x32_bf16 v[94:97], v[146:149], v[230:233], v[94:97]
	v_mfma_f32_16x16x32_bf16 v[90:93], v[150:153], v[226:229], v[90:93]
	v_mfma_f32_16x16x32_bf16 v[90:93], v[158:161], v[230:233], v[90:93]
	v_mfma_f32_16x16x32_bf16 v[78:81], v[138:141], v[234:237], v[78:81]
	v_mfma_f32_16x16x32_bf16 v[78:81], v[146:149], v[238:241], v[78:81]
	v_mfma_f32_16x16x32_bf16 v[74:77], v[150:153], v[234:237], v[74:77]
	v_mfma_f32_16x16x32_bf16 v[74:77], v[158:161], v[238:241], v[74:77]
	s_setprio 0
	s_setprio 1
	v_mfma_f32_16x16x32_bf16 v[118:121], v[182:185], v[198:201], v[118:121]
	v_mfma_f32_16x16x32_bf16 v[118:121], v[186:189], v[214:217], v[118:121]
	v_mfma_f32_16x16x32_bf16 v[114:117], v[190:193], v[198:201], v[114:117]
	v_mfma_f32_16x16x32_bf16 v[114:117], v[194:197], v[214:217], v[114:117]
	v_mfma_f32_16x16x32_bf16 v[102:105], v[182:185], v[218:221], v[102:105]
	v_mfma_f32_16x16x32_bf16 v[102:105], v[186:189], v[222:225], v[102:105]
	v_mfma_f32_16x16x32_bf16 v[98:101], v[190:193], v[218:221], v[98:101]
	v_mfma_f32_16x16x32_bf16 v[98:101], v[194:197], v[222:225], v[98:101]
	v_mfma_f32_16x16x32_bf16 v[86:89], v[182:185], v[226:229], v[86:89]
	v_mfma_f32_16x16x32_bf16 v[86:89], v[186:189], v[230:233], v[86:89]
	v_mfma_f32_16x16x32_bf16 v[82:85], v[190:193], v[226:229], v[82:85]
	v_mfma_f32_16x16x32_bf16 v[82:85], v[194:197], v[230:233], v[82:85]
	v_mfma_f32_16x16x32_bf16 v[70:73], v[182:185], v[234:237], v[70:73]
	v_mfma_f32_16x16x32_bf16 v[70:73], v[186:189], v[238:241], v[70:73]
	v_mfma_f32_16x16x32_bf16 v[66:69], v[190:193], v[234:237], v[66:69]
	v_mfma_f32_16x16x32_bf16 v[66:69], v[194:197], v[238:241], v[66:69]
	s_setprio 0
	s_barrier
	ds_read_b128 v[198:201], v157 offset:16384
	ds_read_b128 v[214:217], v157 offset:17408
	ds_read_b128 v[218:221], v157 offset:18432
	ds_read_b128 v[222:225], v157 offset:19456
	ds_read_b128 v[226:229], v157 offset:20480
	ds_read_b128 v[230:233], v157 offset:21504
	ds_read_b128 v[234:237], v157 offset:22528
	ds_read_b128 v[238:241], v157 offset:23552
	v_lshl_add_u64 v[142:143], s[20:21], 0, v[130:131]
	s_add_i32 s20, vcc_lo, s14
	s_mov_b32 m0, s20
	s_nop 0
	global_load_lds_dwordx4 v[142:143], off
	v_lshl_add_u64 v[162:163], v[142:143], 0, s[72:73]
	s_add_i32 m0, s20, 0x2000
	s_add_i32 s20, vcc_hi, s14
	global_load_lds_dwordx4 v[162:163], off
	v_lshl_add_u64 v[162:163], v[142:143], 0, s[28:29]
	s_mov_b32 m0, s20
	s_nop 0
	global_load_lds_dwordx4 v[162:163], off
	v_lshl_add_u64 v[162:163], v[142:143], 0, s[82:83]
	s_add_i32 m0, s20, 0x2000
	s_nop 0
	global_load_lds_dwordx4 v[162:163], off
	v_lshl_add_u64 v[162:163], s[58:59], 0, v[132:133]
	s_mov_b32 m0, s15
	v_lshl_add_u64 v[202:203], v[162:163], 0, s[72:73]
	global_load_lds_dwordx4 v[162:163], off
	s_mov_b32 m0, s42
	s_nop 0
	global_load_lds_dwordx4 v[202:203], off
	s_waitcnt vmcnt(8)
	s_waitcnt lgkmcnt(0)
	s_barrier
	s_setprio 1
	s_waitcnt lgkmcnt(0)
	v_mfma_f32_16x16x32_bf16 v[62:65], v[138:141], v[198:201], v[62:65]
	v_mfma_f32_16x16x32_bf16 v[62:65], v[146:149], v[214:217], v[62:65]
	v_mfma_f32_16x16x32_bf16 v[58:61], v[150:153], v[198:201], v[58:61]
	v_mfma_f32_16x16x32_bf16 v[58:61], v[158:161], v[214:217], v[58:61]
	v_mfma_f32_16x16x32_bf16 v[46:49], v[138:141], v[218:221], v[46:49]
	v_mfma_f32_16x16x32_bf16 v[46:49], v[146:149], v[222:225], v[46:49]
	v_mfma_f32_16x16x32_bf16 v[42:45], v[150:153], v[218:221], v[42:45]
	v_mfma_f32_16x16x32_bf16 v[42:45], v[158:161], v[222:225], v[42:45]
	v_mfma_f32_16x16x32_bf16 v[30:33], v[138:141], v[226:229], v[30:33]
	v_mfma_f32_16x16x32_bf16 v[30:33], v[146:149], v[230:233], v[30:33]
	v_mfma_f32_16x16x32_bf16 v[26:29], v[150:153], v[226:229], v[26:29]
	v_mfma_f32_16x16x32_bf16 v[26:29], v[158:161], v[230:233], v[26:29]
	v_mfma_f32_16x16x32_bf16 v[14:17], v[138:141], v[234:237], v[14:17]
	v_mfma_f32_16x16x32_bf16 v[14:17], v[146:149], v[238:241], v[14:17]
	v_mfma_f32_16x16x32_bf16 v[10:13], v[150:153], v[234:237], v[10:13]
	v_mfma_f32_16x16x32_bf16 v[10:13], v[158:161], v[238:241], v[10:13]
	s_setprio 0
	s_setprio 1
	v_mfma_f32_16x16x32_bf16 v[54:57], v[182:185], v[198:201], v[54:57]
	v_mfma_f32_16x16x32_bf16 v[54:57], v[186:189], v[214:217], v[54:57]
	v_mfma_f32_16x16x32_bf16 v[50:53], v[190:193], v[198:201], v[50:53]
	v_mfma_f32_16x16x32_bf16 v[50:53], v[194:197], v[214:217], v[50:53]
	v_mfma_f32_16x16x32_bf16 v[38:41], v[182:185], v[218:221], v[38:41]
	v_mfma_f32_16x16x32_bf16 v[38:41], v[186:189], v[222:225], v[38:41]
	v_mfma_f32_16x16x32_bf16 v[34:37], v[190:193], v[218:221], v[34:37]
	v_mfma_f32_16x16x32_bf16 v[34:37], v[194:197], v[222:225], v[34:37]
	v_mfma_f32_16x16x32_bf16 v[22:25], v[182:185], v[226:229], v[22:25]
	v_mfma_f32_16x16x32_bf16 v[22:25], v[186:189], v[230:233], v[22:25]
	v_mfma_f32_16x16x32_bf16 v[18:21], v[190:193], v[226:229], v[18:21]
	v_mfma_f32_16x16x32_bf16 v[18:21], v[194:197], v[230:233], v[18:21]
	v_mfma_f32_16x16x32_bf16 v[6:9], v[182:185], v[234:237], v[6:9]
	v_mfma_f32_16x16x32_bf16 v[6:9], v[186:189], v[238:241], v[6:9]
	v_mfma_f32_16x16x32_bf16 v[2:5], v[190:193], v[234:237], v[2:5]
	v_mfma_f32_16x16x32_bf16 v[2:5], v[194:197], v[238:241], v[2:5]
	s_setprio 0
	s_barrier
	s_add_i32 s20, 0, 0x18000
	v_add_u32_e32 v0, s20, v145
	s_add_i32 s21, 0, 0x1c000
	ds_read_b128 v[138:141], v0
	ds_read_b128 v[146:149], v0 offset:1024
	ds_read_b128 v[150:153], v0 offset:2048
	ds_read_b128 v[158:161], v0 offset:3072
	v_add_u32_e32 v0, s21, v145
	ds_read_b128 v[182:185], v0
	ds_read_b128 v[186:189], v0 offset:1024
	ds_read_b128 v[190:193], v0 offset:2048
	ds_read_b128 v[194:197], v0 offset:3072
	ds_read_b128 v[198:201], v157 offset:32768
	ds_read_b128 v[214:217], v157 offset:33792
	ds_read_b128 v[218:221], v157 offset:34816
	ds_read_b128 v[222:225], v157 offset:35840
	ds_read_b128 v[226:229], v157 offset:36864
	ds_read_b128 v[230:233], v157 offset:37888
	ds_read_b128 v[234:237], v157 offset:38912
	ds_read_b128 v[238:241], v157 offset:39936
	s_mov_b32 m0, s43
	v_lshl_add_u64 v[202:203], v[162:163], 0, s[28:29]
	global_load_lds_dwordx4 v[202:203], off
	v_lshl_add_u64 v[202:203], v[162:163], 0, s[82:83]
	s_mov_b32 m0, s46
	s_nop 0
	global_load_lds_dwordx4 v[202:203], off
	s_waitcnt vmcnt(8)
	s_waitcnt lgkmcnt(0)
	s_barrier
	s_setprio 1
	s_waitcnt lgkmcnt(0)
	v_mfma_f32_16x16x32_bf16 v[126:129], v[138:141], v[198:201], v[126:129]
	v_mfma_f32_16x16x32_bf16 v[126:129], v[146:149], v[214:217], v[126:129]
	v_mfma_f32_16x16x32_bf16 v[122:125], v[150:153], v[198:201], v[122:125]
	v_mfma_f32_16x16x32_bf16 v[122:125], v[158:161], v[214:217], v[122:125]
	v_mfma_f32_16x16x32_bf16 v[110:113], v[138:141], v[218:221], v[110:113]
	v_mfma_f32_16x16x32_bf16 v[110:113], v[146:149], v[222:225], v[110:113]
	v_mfma_f32_16x16x32_bf16 v[106:109], v[150:153], v[218:221], v[106:109]
	v_mfma_f32_16x16x32_bf16 v[106:109], v[158:161], v[222:225], v[106:109]
	v_mfma_f32_16x16x32_bf16 v[94:97], v[138:141], v[226:229], v[94:97]
	v_mfma_f32_16x16x32_bf16 v[94:97], v[146:149], v[230:233], v[94:97]
	v_mfma_f32_16x16x32_bf16 v[90:93], v[150:153], v[226:229], v[90:93]
	v_mfma_f32_16x16x32_bf16 v[90:93], v[158:161], v[230:233], v[90:93]
	v_mfma_f32_16x16x32_bf16 v[78:81], v[138:141], v[234:237], v[78:81]
	v_mfma_f32_16x16x32_bf16 v[78:81], v[146:149], v[238:241], v[78:81]
	v_mfma_f32_16x16x32_bf16 v[74:77], v[150:153], v[234:237], v[74:77]
	v_mfma_f32_16x16x32_bf16 v[74:77], v[158:161], v[238:241], v[74:77]
	s_setprio 0
	s_setprio 1
	v_mfma_f32_16x16x32_bf16 v[118:121], v[182:185], v[198:201], v[118:121]
	v_mfma_f32_16x16x32_bf16 v[118:121], v[186:189], v[214:217], v[118:121]
	v_mfma_f32_16x16x32_bf16 v[114:117], v[190:193], v[198:201], v[114:117]
	v_mfma_f32_16x16x32_bf16 v[114:117], v[194:197], v[214:217], v[114:117]
	v_mfma_f32_16x16x32_bf16 v[102:105], v[182:185], v[218:221], v[102:105]
	v_mfma_f32_16x16x32_bf16 v[102:105], v[186:189], v[222:225], v[102:105]
	v_mfma_f32_16x16x32_bf16 v[98:101], v[190:193], v[218:221], v[98:101]
	v_mfma_f32_16x16x32_bf16 v[98:101], v[194:197], v[222:225], v[98:101]
	v_mfma_f32_16x16x32_bf16 v[86:89], v[182:185], v[226:229], v[86:89]
	v_mfma_f32_16x16x32_bf16 v[86:89], v[186:189], v[230:233], v[86:89]
	v_mfma_f32_16x16x32_bf16 v[82:85], v[190:193], v[226:229], v[82:85]
	v_mfma_f32_16x16x32_bf16 v[82:85], v[194:197], v[230:233], v[82:85]
	v_mfma_f32_16x16x32_bf16 v[70:73], v[182:185], v[234:237], v[70:73]
	v_mfma_f32_16x16x32_bf16 v[70:73], v[186:189], v[238:241], v[70:73]
	v_mfma_f32_16x16x32_bf16 v[66:69], v[190:193], v[234:237], v[66:69]
	v_mfma_f32_16x16x32_bf16 v[66:69], v[194:197], v[238:241], v[66:69]
	s_setprio 0
	s_barrier
	ds_read_b128 v[198:201], v157 offset:49152
	ds_read_b128 v[214:217], v157 offset:50176
	ds_read_b128 v[218:221], v157 offset:51200
	ds_read_b128 v[222:225], v157 offset:52224
	ds_read_b128 v[226:229], v157 offset:53248
	ds_read_b128 v[230:233], v157 offset:54272
	ds_read_b128 v[234:237], v157 offset:55296
	ds_read_b128 v[238:241], v157 offset:56320
	s_add_i32 s20, s20, s14
	v_lshl_add_u64 v[202:203], v[142:143], 0, s[34:35]
	s_mov_b32 m0, s20
	s_nop 0
	global_load_lds_dwordx4 v[202:203], off
	v_lshl_add_u64 v[202:203], v[142:143], 0, s[38:39]
	s_add_i32 m0, s20, 0x2000
	s_add_i32 s20, s21, s14
	global_load_lds_dwordx4 v[202:203], off
	v_lshl_add_u64 v[202:203], v[142:143], 0, s[44:45]
	s_mov_b32 m0, s20
	v_lshl_add_u64 v[142:143], v[142:143], 0, s[10:11]
	global_load_lds_dwordx4 v[202:203], off
	s_add_i32 m0, s20, 0x2000
	s_nop 0
	global_load_lds_dwordx4 v[142:143], off
	v_lshl_add_u64 v[142:143], v[162:163], 0, s[34:35]
	s_mov_b32 m0, s47
	s_nop 0
	global_load_lds_dwordx4 v[142:143], off
	v_lshl_add_u64 v[142:143], v[162:163], 0, s[38:39]
	s_mov_b32 m0, s96
	s_nop 0
	global_load_lds_dwordx4 v[142:143], off
	s_waitcnt vmcnt(8)
	s_waitcnt lgkmcnt(0)
	s_barrier
	s_setprio 1
	s_waitcnt lgkmcnt(0)
	v_mfma_f32_16x16x32_bf16 v[62:65], v[138:141], v[198:201], v[62:65]
	v_mfma_f32_16x16x32_bf16 v[62:65], v[146:149], v[214:217], v[62:65]
	v_mfma_f32_16x16x32_bf16 v[58:61], v[150:153], v[198:201], v[58:61]
	v_mfma_f32_16x16x32_bf16 v[58:61], v[158:161], v[214:217], v[58:61]
	v_mfma_f32_16x16x32_bf16 v[46:49], v[138:141], v[218:221], v[46:49]
	v_mfma_f32_16x16x32_bf16 v[46:49], v[146:149], v[222:225], v[46:49]
	v_mfma_f32_16x16x32_bf16 v[42:45], v[150:153], v[218:221], v[42:45]
	v_mfma_f32_16x16x32_bf16 v[42:45], v[158:161], v[222:225], v[42:45]
	v_mfma_f32_16x16x32_bf16 v[30:33], v[138:141], v[226:229], v[30:33]
	v_mfma_f32_16x16x32_bf16 v[30:33], v[146:149], v[230:233], v[30:33]
	v_mfma_f32_16x16x32_bf16 v[26:29], v[150:153], v[226:229], v[26:29]
	v_mfma_f32_16x16x32_bf16 v[26:29], v[158:161], v[230:233], v[26:29]
	v_mfma_f32_16x16x32_bf16 v[14:17], v[138:141], v[234:237], v[14:17]
	v_mfma_f32_16x16x32_bf16 v[14:17], v[146:149], v[238:241], v[14:17]
	v_mfma_f32_16x16x32_bf16 v[10:13], v[150:153], v[234:237], v[10:13]
	v_mfma_f32_16x16x32_bf16 v[10:13], v[158:161], v[238:241], v[10:13]
	s_add_i32 s91, s91, 2
	s_add_u32 s56, s56, 0x100
	s_addc_u32 s57, s57, 0
	s_add_u32 s86, s86, 0x100
	s_addc_u32 s87, s87, 0
	s_setprio 0
	s_setprio 1
	v_mfma_f32_16x16x32_bf16 v[54:57], v[182:185], v[198:201], v[54:57]
	v_mfma_f32_16x16x32_bf16 v[54:57], v[186:189], v[214:217], v[54:57]
	v_mfma_f32_16x16x32_bf16 v[50:53], v[190:193], v[198:201], v[50:53]
	v_mfma_f32_16x16x32_bf16 v[50:53], v[194:197], v[214:217], v[50:53]
	v_mfma_f32_16x16x32_bf16 v[38:41], v[182:185], v[218:221], v[38:41]
	v_mfma_f32_16x16x32_bf16 v[38:41], v[186:189], v[222:225], v[38:41]
	v_mfma_f32_16x16x32_bf16 v[34:37], v[190:193], v[218:221], v[34:37]
	v_mfma_f32_16x16x32_bf16 v[34:37], v[194:197], v[222:225], v[34:37]
	v_mfma_f32_16x16x32_bf16 v[22:25], v[182:185], v[226:229], v[22:25]
	v_mfma_f32_16x16x32_bf16 v[22:25], v[186:189], v[230:233], v[22:25]
	v_mfma_f32_16x16x32_bf16 v[18:21], v[190:193], v[226:229], v[18:21]
	v_mfma_f32_16x16x32_bf16 v[18:21], v[194:197], v[230:233], v[18:21]
	v_mfma_f32_16x16x32_bf16 v[6:9], v[182:185], v[234:237], v[6:9]
	v_mfma_f32_16x16x32_bf16 v[6:9], v[186:189], v[238:241], v[6:9]
	v_mfma_f32_16x16x32_bf16 v[2:5], v[190:193], v[234:237], v[2:5]
	v_mfma_f32_16x16x32_bf16 v[2:5], v[194:197], v[238:241], v[2:5]
	s_setprio 0
	s_barrier
	s_cmp_gt_u32 s91, 13
	s_cbranch_scc0 .LBB0_850
	s_and_b64 vcc, exec, s[62:63]
	s_cbranch_vccz .LBB0_853
	s_barrier
